# out-proj GEMM epilogues: residual/base and modulation loads marked non-temporal
# speedup vs baseline: 1.0157x; 1.0024x over previous
; __device__ __forceinline__ unsigned cvt_pk_bf16(float lo, float hi) { unsigned r; asm volatile("v_cvt_pk_bf16_f32 %0, %1, %2" : "=v"(r) : "v"(lo), "v"(hi)); return r; }
;     __device__ __forceinline__ void operator()(const f32x4 (&acc)[2][2][4][2], const Unit& u, int wr, int wc, int fr, int fq) const {
;         const int hi8 = fr >> 3;
;         const int rowA = u.pm * BM + wr * 64 + (fr & 7), rowB = rowA + 8; const int col0 = u.pn * BM + wc * 32 + 16 * hi8 + 4 * fq;
;         const size_t bofs = (size_t)((u.pm * BM) / 8192) * 3072 + col0;
;         f32x4 gs[2], av[2];
; #pragma unroll
;         for (int bj = 0; bj < 2; ++bj) { gs[bj] = *(const f32x4*)(gate + bofs + bj * HALF); av[bj] = *(const f32x4*)(ng + col0 + bj * HALF) * (*(const f32x4*)(scl + bofs + bj * HALF) + 1.f); }
; #pragma unroll
;         for (int ai = 0; ai < 2; ++ai)
; #pragma unroll
;             for (int m = 0; m < 4; ++m) { const int ra = rowA + ai * HALF + m * 16, rb = rowB + ai * HALF + m * 16; const size_t offA = (size_t)ra * 1024 + col0, offB = (size_t)rb * 1024 + col0;
;                 float ssa = 0.f, ssb = 0.f;
; #pragma unroll
;                 for (int bj = 0; bj < 2; ++bj) {
;                     const f32x4 x0 = acc[ai][bj][m][0], x1 = acc[ai][bj][m][1]; f32x4 za, zb;
; #pragma unroll
;                     for (int e = 0; e < 4; ++e) { const float s1 = __shfl_xor(x1[e], 8), s0 = __shfl_xor(x0[e], 8); za[e] = hi8 ? s1 : x0[e]; zb[e] = hi8 ? x1[e] : s0; }
;                     const f32x4 ba = *(const f32x4*)(base + offA + bj * HALF), bb = *(const f32x4*)(base + offB + bj * HALF);
;                     const f32x4 oa = ba + gs[bj] * za, ob = bb + gs[bj] * zb;
;                     *(f32x4*)(out + offA + bj * HALF) = oa; *(f32x4*)(out + offB + bj * HALF) = ob;
;                     const f32x4 ha = oa * av[bj], hb = ob * av[bj];
;                     *(unsigned long long*)(Hn + offA + bj * HALF) = (unsigned long long)cvt_pk_bf16(ha[0], ha[1]) | ((unsigned long long)cvt_pk_bf16(ha[2], ha[3]) << 32);
;                     *(unsigned long long*)(Hn + offB + bj * HALF) = (unsigned long long)cvt_pk_bf16(hb[0], hb[1]) | ((unsigned long long)cvt_pk_bf16(hb[2], hb[3]) << 32);
;                     ssa += (oa[0] * oa[0] + oa[1] * oa[1]) + (oa[2] * oa[2] + oa[3] * oa[3]); ssb += (ob[0] * ob[0] + ob[1] * ob[1]) + (ob[2] * ob[2] + ob[3] * ob[3]); }
.LBB0_543:
	s_ashr_i32 s21, s28, 31
	v_lshl_add_u32 v150, s28, 8, v155
	s_lshr_b32 s21, s21, 27
	v_lshl_add_u32 v148, s30, 8, v156
	s_add_i32 s21, s28, s21
	v_or_b32_e32 v152, 8, v150
	v_readlane_b32 s52, v252, 18
	s_ashr_i32 s21, s21, 5
	v_ashrrev_i32_e32 v149, 31, v148
	v_ashrrev_i32_e32 v151, 31, v150
	v_ashrrev_i32_e32 v153, 31, v152
	v_readlane_b32 s53, v252, 19
	v_readlane_b32 s54, v252, 20
	v_readlane_b32 s55, v252, 21
	v_readlane_b32 s56, v252, 22
	v_readlane_b32 s57, v252, 23
	v_readlane_b32 s58, v252, 24
	v_readlane_b32 s59, v252, 25
	v_readlane_b32 s60, v252, 26
	v_readlane_b32 s61, v252, 27
	v_readlane_b32 s62, v252, 28
	v_readlane_b32 s63, v252, 29
	v_readlane_b32 s64, v252, 30
	v_readlane_b32 s65, v252, 31
	v_readlane_b32 s66, v252, 32
	v_readlane_b32 s67, v252, 33
	v_mad_i64_i32 v[48:49], s[28:29], s21, v161, v[148:149]
	v_lshlrev_b64 v[54:55], 10, v[150:151]
	v_lshlrev_b64 v[162:163], 10, v[152:153]
	s_mov_b64 s[36:37], s[52:53]
	v_readlane_b32 s52, v252, 2
	v_lshlrev_b64 v[48:49], 2, v[48:49]
	v_lshl_add_u64 v[54:55], v[54:55], 0, v[148:149]
	v_lshl_add_u64 v[186:187], v[162:163], 0, v[148:149]
	v_readlane_b32 s53, v252, 3
	v_readlane_b32 s56, v252, 6
	v_readlane_b32 s57, v252, 7
	v_lshl_add_u64 v[52:53], s[10:11], 0, v[48:49]
	v_lshlrev_b64 v[188:189], 2, v[54:55]
	v_lshlrev_b64 v[192:193], 2, v[186:187]
	s_mov_b64 s[52:53], s[56:57]
	v_lshl_add_u64 v[184:185], s[12:13], 0, v[48:49]
	global_load_dwordx4 v[48:51], v[52:53], off nt
	global_load_dwordx4 v[164:167], v[184:185], off nt
	v_lshl_add_u64 v[190:191], s[36:37], 0, v[188:189]
	v_lshl_add_u64 v[194:195], s[36:37], 0, v[192:193]
	v_lshl_add_u64 v[162:163], v[148:149], 2, s[52:53]
	global_load_dwordx4 v[168:171], v[190:191], off nt
	global_load_dwordx4 v[172:175], v[194:195], off nt
	global_load_dwordx4 v[176:179], v[162:163], off nt
	v_and_b32_e32 v181, 64, v160
	v_xor_b32_e32 v180, 8, v160
	v_add_u32_e32 v204, 64, v181
	v_cmp_lt_i32_e32 vcc, v180, v204
	v_readlane_b32 s62, v252, 12
	v_readlane_b32 s63, v252, 13
	v_cndmask_b32_e32 v196, v160, v180, vcc
	global_load_dwordx4 v[180:183], v[162:163], off offset:512 nt
	v_lshlrev_b32_e32 v162, 2, v196
	ds_bpermute_b32 v163, v162, v128
	ds_bpermute_b32 v200, v162, v132
	ds_bpermute_b32 v201, v162, v129
	ds_bpermute_b32 v202, v162, v133
	ds_bpermute_b32 v203, v162, v130
	ds_bpermute_b32 v205, v162, v134
	ds_bpermute_b32 v206, v162, v131
	ds_bpermute_b32 v207, v162, v135
	v_readlane_b32 s66, v252, 16
	v_readlane_b32 s67, v252, 17
	s_waitcnt lgkmcnt(0)
	v_cndmask_b32_e64 v132, v163, v132, s[0:1]
	v_cndmask_b32_e64 v128, v128, v200, s[0:1]
	v_cndmask_b32_e64 v133, v201, v133, s[0:1]
	v_cndmask_b32_e64 v129, v129, v202, s[0:1]
	v_cndmask_b32_e64 v134, v203, v134, s[0:1]
	v_cndmask_b32_e64 v130, v130, v205, s[0:1]
	v_cndmask_b32_e64 v135, v206, v135, s[0:1]
	v_cndmask_b32_e64 v131, v131, v207, s[0:1]
	s_mov_b64 s[62:63], s[66:67]
	v_lshl_add_u64 v[196:197], v[54:55], 1, s[4:5]
	v_lshl_add_u64 v[188:189], s[62:63], 0, v[188:189]
	v_lshl_add_u64 v[198:199], v[186:187], 1, s[4:5]
	v_lshl_add_u64 v[192:193], s[62:63], 0, v[192:193]
	global_load_dwordx4 v[52:55], v[52:53], off offset:512 nt
	s_nop 0
	global_load_dwordx4 v[184:187], v[184:185], off offset:512 nt
	ds_bpermute_b32 v163, v162, v121
	v_readlane_b32 s54, v252, 4
	v_readlane_b32 s55, v252, 5
	v_readlane_b32 s58, v252, 8
	v_readlane_b32 s59, v252, 9
	v_readlane_b32 s60, v252, 10
	v_readlane_b32 s61, v252, 11
	v_readlane_b32 s64, v252, 14
	v_readlane_b32 s65, v252, 15
	s_waitcnt vmcnt(0)
	v_pk_add_f32 v[200:201], v[166:167], 1.0 op_sel_hi:[1,0]
	v_pk_add_f32 v[202:203], v[164:165], 1.0 op_sel_hi:[1,0]
	v_pk_fma_f32 v[166:167], v[50:51], v[134:135], v[170:171]
	v_pk_fma_f32 v[164:165], v[48:49], v[132:133], v[168:169]
	v_pk_fma_f32 v[170:171], v[50:51], v[130:131], v[174:175]
	v_pk_fma_f32 v[168:169], v[48:49], v[128:129], v[172:173]
	v_pk_mul_f32 v[128:129], v[178:179], v[200:201]
	v_pk_mul_f32 v[130:131], v[176:177], v[202:203]
	v_pk_mul_f32 v[132:133], v[128:129], v[166:167]
	v_pk_mul_f32 v[134:135], v[130:131], v[164:165]
	global_store_dwordx4 v[188:189], v[164:167], off sc1
	global_store_dwordx4 v[192:193], v[168:171], off sc1
	v_pk_mul_f32 v[172:173], v[128:129], v[170:171]
	v_pk_mul_f32 v[174:175], v[130:131], v[168:169]
	v_cvt_pk_bf16_f32 v134, v134, v135
	v_cvt_pk_bf16_f32 v135, v132, v133
	global_store_dwordx2 v[196:197], v[134:135], off
	v_cvt_pk_bf16_f32 v132, v174, v175
	v_cvt_pk_bf16_f32 v133, v172, v173
	global_store_dwordx2 v[198:199], v[132:133], off
	global_load_dwordx4 v[172:175], v[190:191], off offset:512 nt
	global_load_dwordx4 v[176:179], v[194:195], off offset:512 nt
	v_xor_b32_e32 v132, 16, v160
	v_xor_b32_e32 v133, 32, v160
	v_cmp_lt_i32_e32 vcc, v132, v204
	ds_bpermute_b32 v135, v162, v124
	ds_bpermute_b32 v190, v162, v125
	v_cndmask_b32_e32 v132, v160, v132, vcc
	v_cmp_lt_i32_e32 vcc, v133, v204
	ds_bpermute_b32 v191, v162, v122
	ds_bpermute_b32 v194, v162, v126
	v_cndmask_b32_e32 v134, v160, v133, vcc
	v_lshlrev_b32_e32 v133, 2, v132
	v_lshlrev_b32_e32 v132, 2, v134
	ds_bpermute_b32 v134, v162, v120
	ds_bpermute_b32 v195, v162, v123
	ds_bpermute_b32 v200, v162, v127
	s_waitcnt lgkmcnt(7)
	v_cndmask_b32_e64 v125, v163, v125, s[0:1]
	v_mul_f32_e32 v163, v165, v165
	v_mul_f32_e32 v165, v167, v167
	v_mul_f32_e32 v167, v169, v169
	v_mul_f32_e32 v169, v171, v171
	s_waitcnt lgkmcnt(2)
	v_cndmask_b32_e64 v124, v134, v124, s[0:1]
	v_cndmask_b32_e64 v134, v120, v135, s[0:1]
	v_cndmask_b32_e64 v135, v121, v190, s[0:1]
	v_cndmask_b32_e64 v126, v191, v126, s[0:1]
	v_cndmask_b32_e64 v190, v122, v194, s[0:1]
	s_waitcnt lgkmcnt(1)
; __device__ __forceinline__ unsigned cvt_pk_bf16(float lo, float hi) { unsigned r; asm volatile("v_cvt_pk_bf16_f32 %0, %1, %2" : "=v"(r) : "v"(lo), "v"(hi)); return r; }
;     __device__ __forceinline__ void operator()(const f32x4 (&acc)[2][2][4][2], const Unit& u, int wr, int wc, int fr, int fq) const {
;     ...
;             for (int m = 0; m < 4; ++m) { const int ra = rowA + ai * HALF + m * 16, rb = rowB + ai * HALF + m * 16; const size_t offA = (size_t)ra * 1024 + col0, offB = (size_t)rb * 1024 + col0;
;                 float ssa = 0.f, ssb = 0.f;
; #pragma unroll
;                 for (int bj = 0; bj < 2; ++bj) {
;                     const f32x4 x0 = acc[ai][bj][m][0], x1 = acc[ai][bj][m][1]; f32x4 za, zb;
; #pragma unroll
;                     for (int e = 0; e < 4; ++e) { const float s1 = __shfl_xor(x1[e], 8), s0 = __shfl_xor(x0[e], 8); za[e] = hi8 ? s1 : x0[e]; zb[e] = hi8 ? x1[e] : s0; }
;                     const f32x4 ba = *(const f32x4*)(base + offA + bj * HALF), bb = *(const f32x4*)(base + offB + bj * HALF);
;                     const f32x4 oa = ba + gs[bj] * za, ob = bb + gs[bj] * zb;
;                     *(f32x4*)(out + offA + bj * HALF) = oa; *(f32x4*)(out + offB + bj * HALF) = ob;
;                     const f32x4 ha = oa * av[bj], hb = ob * av[bj];
;                     *(unsigned long long*)(Hn + offA + bj * HALF) = (unsigned long long)cvt_pk_bf16(ha[0], ha[1]) | ((unsigned long long)cvt_pk_bf16(ha[2], ha[3]) << 32);
;                     *(unsigned long long*)(Hn + offB + bj * HALF) = (unsigned long long)cvt_pk_bf16(hb[0], hb[1]) | ((unsigned long long)cvt_pk_bf16(hb[2], hb[3]) << 32);
;                     ssa += (oa[0] * oa[0] + oa[1] * oa[1]) + (oa[2] * oa[2] + oa[3] * oa[3]); ssb += (ob[0] * ob[0] + ob[1] * ob[1]) + (ob[2] * ob[2] + ob[3] * ob[3]); }
;                 ssa += __shfl_xor(ssa, 8); ssa += __shfl_xor(ssa, 16); ssa += __shfl_xor(ssa, 32);
;                 ssb += __shfl_xor(ssb, 8); ssb += __shfl_xor(ssb, 16); ssb += __shfl_xor(ssb, 32);
;                 if (fq == 0 && hi8 == 0) { atomicAdd(rowss + ra, ssa); atomicAdd(rowss + rb, ssb); } }
	v_cndmask_b32_e64 v127, v195, v127, s[0:1]
	s_waitcnt lgkmcnt(0)
	v_cndmask_b32_e64 v191, v123, v200, s[0:1]
	v_fmac_f32_e32 v163, v164, v164
	v_fmac_f32_e32 v165, v166, v166
	v_fmac_f32_e32 v167, v168, v168
	v_fmac_f32_e32 v169, v170, v170
	v_add_f32_e32 v163, v163, v165
	v_add_f32_e32 v168, v167, v169
	v_pk_add_f32 v[120:121], v[186:187], 1.0 op_sel_hi:[1,0]
	v_pk_add_f32 v[184:185], v[184:185], 1.0 op_sel_hi:[1,0]
	v_pk_mul_f32 v[122:123], v[182:183], v[120:121]
	v_pk_mul_f32 v[120:121], v[180:181], v[184:185]
	s_waitcnt vmcnt(1)
	v_pk_fma_f32 v[126:127], v[54:55], v[126:127], v[174:175]
	v_pk_fma_f32 v[124:125], v[52:53], v[124:125], v[172:173]
	s_waitcnt vmcnt(0)
	v_pk_fma_f32 v[166:167], v[54:55], v[190:191], v[178:179]
	v_pk_fma_f32 v[164:165], v[52:53], v[134:135], v[176:177]
	v_mul_f32_e32 v134, v125, v125
	v_mul_f32_e32 v135, v127, v127
	v_mul_f32_e32 v169, v165, v165
	v_mul_f32_e32 v170, v167, v167
	v_fmac_f32_e32 v134, v124, v124
	v_fmac_f32_e32 v135, v126, v126
	v_fmac_f32_e32 v169, v164, v164
	v_fmac_f32_e32 v170, v166, v166
	v_add_f32_e32 v134, v134, v135
	v_add_f32_e32 v135, v169, v170
	v_add_f32_e32 v163, v163, v134
	v_add_f32_e32 v168, v168, v135
	ds_bpermute_b32 v169, v162, v163
	ds_bpermute_b32 v170, v162, v168
	global_store_dwordx4 v[188:189], v[124:127], off offset:512 sc1
	global_store_dwordx4 v[192:193], v[164:167], off offset:512 sc1
	v_pk_mul_f32 v[134:135], v[122:123], v[166:167]
	v_pk_mul_f32 v[124:125], v[120:121], v[124:125]
	s_waitcnt lgkmcnt(1)
	v_add_f32_e32 v163, v163, v169
	s_waitcnt lgkmcnt(0)
	v_add_f32_e32 v168, v168, v170
	ds_bpermute_b32 v169, v133, v163
	ds_bpermute_b32 v170, v133, v168
	v_pk_mul_f32 v[126:127], v[122:123], v[126:127]
	v_cvt_pk_bf16_f32 v166, v124, v125
	v_pk_mul_f32 v[164:165], v[120:121], v[164:165]
	s_waitcnt lgkmcnt(1)
	v_add_f32_e32 v124, v163, v169
	s_waitcnt lgkmcnt(0)
	v_add_f32_e32 v125, v168, v170
	v_cvt_pk_bf16_f32 v167, v126, v127
	ds_bpermute_b32 v126, v132, v124
	ds_bpermute_b32 v127, v132, v125
	global_store_dwordx2 v[196:197], v[166:167], off offset:256
	v_cvt_pk_bf16_f32 v164, v164, v165
	v_cvt_pk_bf16_f32 v165, v134, v135
	global_store_dwordx2 v[198:199], v[164:165], off offset:256
	s_and_saveexec_b64 s[28:29], s[18:19]
	s_cbranch_execz .LBB0_545
	v_lshl_add_u64 v[134:135], v[152:153], 2, s[68:69]
	v_lshl_add_u64 v[152:153], v[150:151], 2, s[68:69]
	s_waitcnt lgkmcnt(1)
	v_add_f32_e32 v124, v124, v126
	s_waitcnt lgkmcnt(0)
	v_add_f32_e32 v125, v125, v127
	global_atomic_add_f32 v[152:153], v124, off
	global_atomic_add_f32 v[134:135], v125, off
.LBB0_545:
	s_or_b64 exec, exec, s[28:29]
	v_or_b32_e32 v124, 16, v150
	s_waitcnt lgkmcnt(1)
	v_or_b32_e32 v126, 24, v150
	v_ashrrev_i32_e32 v125, 31, v124
	v_lshlrev_b64 v[134:135], 10, v[124:125]
	s_waitcnt lgkmcnt(0)
	v_ashrrev_i32_e32 v127, 31, v126
	v_readlane_b32 s52, v252, 18
	v_lshl_add_u64 v[134:135], v[134:135], 0, v[148:149]
	v_lshlrev_b64 v[152:153], 10, v[126:127]
	v_readlane_b32 s53, v252, 19
	v_lshl_add_u64 v[152:153], v[152:153], 0, v[148:149]
	v_lshlrev_b64 v[172:173], 2, v[134:135]
	s_mov_b64 s[36:37], s[52:53]
	v_lshl_add_u64 v[174:175], s[36:37], 0, v[172:173]
	v_lshlrev_b64 v[176:177], 2, v[152:153]
	global_load_dwordx4 v[164:167], v[174:175], off nt
	v_lshl_add_u64 v[178:179], s[36:37], 0, v[176:177]
	global_load_dwordx4 v[168:171], v[178:179], off nt
	ds_bpermute_b32 v151, v162, v112
	ds_bpermute_b32 v163, v162, v116
	ds_bpermute_b32 v181, v162, v113
	ds_bpermute_b32 v182, v162, v117
	ds_bpermute_b32 v183, v162, v114
	ds_bpermute_b32 v185, v162, v115
	ds_bpermute_b32 v184, v162, v118
	ds_bpermute_b32 v186, v162, v119
	v_readlane_b32 s54, v252, 20
	v_readlane_b32 s55, v252, 21
	v_readlane_b32 s56, v252, 22
	v_readlane_b32 s57, v252, 23
	v_readlane_b32 s58, v252, 24
	v_readlane_b32 s59, v252, 25
	v_readlane_b32 s60, v252, 26
	v_readlane_b32 s61, v252, 27
	v_readlane_b32 s62, v252, 28
	v_readlane_b32 s63, v252, 29
	v_readlane_b32 s64, v252, 30
	v_readlane_b32 s65, v252, 31
	v_readlane_b32 s66, v252, 32
	v_readlane_b32 s67, v252, 33
	v_readlane_b32 s52, v252, 2
	s_waitcnt lgkmcnt(7)
	v_cndmask_b32_e64 v116, v151, v116, s[0:1]
	s_waitcnt lgkmcnt(6)
	v_cndmask_b32_e64 v180, v112, v163, s[0:1]
	s_waitcnt lgkmcnt(5)
	v_cndmask_b32_e64 v117, v181, v117, s[0:1]
	s_waitcnt lgkmcnt(4)
	v_cndmask_b32_e64 v181, v113, v182, s[0:1]
	s_waitcnt lgkmcnt(3)
	v_cndmask_b32_e64 v112, v183, v118, s[0:1]
	s_waitcnt lgkmcnt(2)
	v_cndmask_b32_e64 v113, v185, v119, s[0:1]
	v_readlane_b32 s62, v252, 12
	v_readlane_b32 s63, v252, 13
	v_readlane_b32 s66, v252, 16
	v_readlane_b32 s67, v252, 17
	s_waitcnt lgkmcnt(1)
	v_cndmask_b32_e64 v118, v114, v184, s[0:1]
	s_waitcnt lgkmcnt(0)
	v_cndmask_b32_e64 v119, v115, v186, s[0:1]
	s_mov_b64 s[62:63], s[66:67]
	v_lshl_add_u64 v[134:135], v[134:135], 1, s[4:5]
	v_lshl_add_u64 v[152:153], v[152:153], 1, s[4:5]
	v_lshl_add_u64 v[172:173], s[62:63], 0, v[172:173]
	v_lshl_add_u64 v[176:177], s[62:63], 0, v[176:177]
	ds_bpermute_b32 v163, v162, v108
	ds_bpermute_b32 v182, v162, v111
	ds_bpermute_b32 v151, v162, v104
	v_readlane_b32 s53, v252, 3
	v_readlane_b32 s54, v252, 4
	v_readlane_b32 s55, v252, 5
	v_readlane_b32 s56, v252, 6
	s_waitcnt lgkmcnt(0)
	v_cndmask_b32_e64 v108, v151, v108, s[0:1]
	v_readlane_b32 s57, v252, 7
	v_readlane_b32 s58, v252, 8
	v_readlane_b32 s59, v252, 9
	v_readlane_b32 s60, v252, 10
	v_readlane_b32 s61, v252, 11
	v_readlane_b32 s64, v252, 14
	v_readlane_b32 s65, v252, 15
	s_waitcnt vmcnt(1)
	v_pk_fma_f32 v[114:115], v[50:51], v[112:113], v[166:167]
	v_pk_fma_f32 v[112:113], v[48:49], v[116:117], v[164:165]
	s_waitcnt vmcnt(0)
; __device__ __forceinline__ unsigned cvt_pk_bf16(float lo, float hi) { unsigned r; asm volatile("v_cvt_pk_bf16_f32 %0, %1, %2" : "=v"(r) : "v"(lo), "v"(hi)); return r; }
;     __device__ __forceinline__ void operator()(const f32x4 (&acc)[2][2][4][2], const Unit& u, int wr, int wc, int fr, int fq) const {
;     ...
;             for (int m = 0; m < 4; ++m) { const int ra = rowA + ai * HALF + m * 16, rb = rowB + ai * HALF + m * 16; const size_t offA = (size_t)ra * 1024 + col0, offB = (size_t)rb * 1024 + col0;
;                 float ssa = 0.f, ssb = 0.f;
; #pragma unroll
;                 for (int bj = 0; bj < 2; ++bj) {
;                     const f32x4 x0 = acc[ai][bj][m][0], x1 = acc[ai][bj][m][1]; f32x4 za, zb;
; #pragma unroll
;                     for (int e = 0; e < 4; ++e) { const float s1 = __shfl_xor(x1[e], 8), s0 = __shfl_xor(x0[e], 8); za[e] = hi8 ? s1 : x0[e]; zb[e] = hi8 ? x1[e] : s0; }
;                     const f32x4 ba = *(const f32x4*)(base + offA + bj * HALF), bb = *(const f32x4*)(base + offB + bj * HALF);
;                     const f32x4 oa = ba + gs[bj] * za, ob = bb + gs[bj] * zb;
;                     *(f32x4*)(out + offA + bj * HALF) = oa; *(f32x4*)(out + offB + bj * HALF) = ob;
;                     const f32x4 ha = oa * av[bj], hb = ob * av[bj];
;                     *(unsigned long long*)(Hn + offA + bj * HALF) = (unsigned long long)cvt_pk_bf16(ha[0], ha[1]) | ((unsigned long long)cvt_pk_bf16(ha[2], ha[3]) << 32);
;                     *(unsigned long long*)(Hn + offB + bj * HALF) = (unsigned long long)cvt_pk_bf16(hb[0], hb[1]) | ((unsigned long long)cvt_pk_bf16(hb[2], hb[3]) << 32);
;                     ssa += (oa[0] * oa[0] + oa[1] * oa[1]) + (oa[2] * oa[2] + oa[3] * oa[3]); ssb += (ob[0] * ob[0] + ob[1] * ob[1]) + (ob[2] * ob[2] + ob[3] * ob[3]); }
;                 ssa += __shfl_xor(ssa, 8); ssa += __shfl_xor(ssa, 16); ssa += __shfl_xor(ssa, 32);
;                 ssb += __shfl_xor(ssb, 8); ssb += __shfl_xor(ssb, 16); ssb += __shfl_xor(ssb, 32);
;                 if (fq == 0 && hi8 == 0) { atomicAdd(rowss + ra, ssa); atomicAdd(rowss + rb, ssb); } }
	v_pk_fma_f32 v[118:119], v[50:51], v[118:119], v[170:171]
	v_pk_fma_f32 v[116:117], v[48:49], v[180:181], v[168:169]
	v_pk_mul_f32 v[164:165], v[128:129], v[114:115]
	v_pk_mul_f32 v[166:167], v[130:131], v[112:113]
	global_store_dwordx4 v[172:173], v[112:115], off sc1
	global_store_dwordx4 v[176:177], v[116:119], off sc1
	v_pk_mul_f32 v[168:169], v[128:129], v[118:119]
	v_pk_mul_f32 v[170:171], v[130:131], v[116:117]
	v_cvt_pk_bf16_f32 v166, v166, v167
	v_cvt_pk_bf16_f32 v167, v164, v165
	global_store_dwordx2 v[134:135], v[166:167], off
	v_cvt_pk_bf16_f32 v164, v170, v171
	v_cvt_pk_bf16_f32 v165, v168, v169
	global_store_dwordx2 v[152:153], v[164:165], off
	global_load_dwordx4 v[164:167], v[174:175], off offset:512 nt
	s_nop 0
	global_load_dwordx4 v[168:171], v[178:179], off offset:512 nt
	ds_bpermute_b32 v175, v162, v105
	ds_bpermute_b32 v178, v162, v109
	ds_bpermute_b32 v179, v162, v106
	ds_bpermute_b32 v180, v162, v110
	ds_bpermute_b32 v181, v162, v107
	v_cndmask_b32_e64 v174, v104, v163, s[0:1]
	s_waitcnt lgkmcnt(4)
	v_cndmask_b32_e64 v109, v175, v109, s[0:1]
	s_waitcnt lgkmcnt(3)
	v_cndmask_b32_e64 v175, v105, v178, s[0:1]
	s_waitcnt lgkmcnt(2)
	v_cndmask_b32_e64 v104, v179, v110, s[0:1]
	s_waitcnt lgkmcnt(1)
	v_cndmask_b32_e64 v110, v106, v180, s[0:1]
	s_waitcnt lgkmcnt(0)
	v_cndmask_b32_e64 v105, v181, v111, s[0:1]
	v_cndmask_b32_e64 v111, v107, v182, s[0:1]
	v_mul_f32_e32 v106, v113, v113
	v_mul_f32_e32 v107, v115, v115
	v_mul_f32_e32 v113, v117, v117
	v_mul_f32_e32 v115, v119, v119
	v_fmac_f32_e32 v106, v112, v112
	v_fmac_f32_e32 v107, v114, v114
	v_fmac_f32_e32 v113, v116, v116
	v_fmac_f32_e32 v115, v118, v118
	v_add_f32_e32 v112, v106, v107
	v_add_f32_e32 v113, v113, v115
	s_waitcnt vmcnt(1)
	v_pk_fma_f32 v[106:107], v[54:55], v[104:105], v[166:167]
	v_pk_fma_f32 v[104:105], v[52:53], v[108:109], v[164:165]
	s_waitcnt vmcnt(0)
	v_pk_fma_f32 v[110:111], v[54:55], v[110:111], v[170:171]
	v_pk_fma_f32 v[108:109], v[52:53], v[174:175], v[168:169]
	v_mul_f32_e32 v114, v105, v105
	v_mul_f32_e32 v115, v107, v107
	v_mul_f32_e32 v116, v109, v109
	v_mul_f32_e32 v117, v111, v111
	v_fmac_f32_e32 v114, v104, v104
	v_fmac_f32_e32 v115, v106, v106
	v_fmac_f32_e32 v116, v108, v108
	v_fmac_f32_e32 v117, v110, v110
	v_add_f32_e32 v114, v114, v115
	v_add_f32_e32 v115, v116, v117
	v_add_f32_e32 v112, v112, v114
	v_add_f32_e32 v113, v113, v115
	ds_bpermute_b32 v114, v162, v112
	ds_bpermute_b32 v115, v162, v113
	global_store_dwordx4 v[172:173], v[104:107], off offset:512 sc1
	global_store_dwordx4 v[176:177], v[108:111], off offset:512 sc1
	s_waitcnt lgkmcnt(1)
	v_add_f32_e32 v114, v112, v114
	s_waitcnt lgkmcnt(0)
	v_add_f32_e32 v115, v113, v115
	ds_bpermute_b32 v116, v133, v114
	ds_bpermute_b32 v117, v133, v115
	v_pk_mul_f32 v[104:105], v[120:121], v[104:105]
	v_pk_mul_f32 v[106:107], v[122:123], v[106:107]
	v_cvt_pk_bf16_f32 v112, v104, v105
	s_waitcnt lgkmcnt(1)
	v_add_f32_e32 v104, v114, v116
	s_waitcnt lgkmcnt(0)
	v_add_f32_e32 v105, v115, v117
	v_cvt_pk_bf16_f32 v113, v106, v107
	ds_bpermute_b32 v106, v132, v104
	ds_bpermute_b32 v107, v132, v105
	v_pk_mul_f32 v[108:109], v[120:121], v[108:109]
	v_pk_mul_f32 v[110:111], v[122:123], v[110:111]
	global_store_dwordx2 v[134:135], v[112:113], off offset:256
	v_cvt_pk_bf16_f32 v108, v108, v109
	v_cvt_pk_bf16_f32 v109, v110, v111
	global_store_dwordx2 v[152:153], v[108:109], off offset:256
	s_and_saveexec_b64 s[28:29], s[18:19]
	s_cbranch_execz .LBB0_547
	v_lshl_add_u64 v[110:111], v[124:125], 2, s[68:69]
	s_waitcnt lgkmcnt(1)
	v_add_f32_e32 v104, v104, v106
	v_lshl_add_u64 v[108:109], v[126:127], 2, s[68:69]
	s_waitcnt lgkmcnt(0)
	v_add_f32_e32 v105, v105, v107
	global_atomic_add_f32 v[110:111], v104, off
	global_atomic_add_f32 v[108:109], v105, off
.LBB0_547:
	s_or_b64 exec, exec, s[28:29]
	v_or_b32_e32 v104, 32, v150
	s_waitcnt lgkmcnt(1)
	v_or_b32_e32 v106, 40, v150
	v_ashrrev_i32_e32 v105, 31, v104
	v_lshlrev_b64 v[108:109], 10, v[104:105]
	s_waitcnt lgkmcnt(0)
	v_ashrrev_i32_e32 v107, 31, v106
	v_readlane_b32 s52, v252, 18
	v_lshl_add_u64 v[116:117], v[108:109], 0, v[148:149]
	v_lshlrev_b64 v[108:109], 10, v[106:107]
	v_readlane_b32 s53, v252, 19
	v_lshl_add_u64 v[118:119], v[108:109], 0, v[148:149]
	v_lshlrev_b64 v[124:125], 2, v[116:117]
	s_mov_b64 s[36:37], s[52:53]
	v_lshl_add_u64 v[126:127], s[36:37], 0, v[124:125]
	v_lshlrev_b64 v[134:135], 2, v[118:119]
	global_load_dwordx4 v[108:111], v[126:127], off nt
	v_lshl_add_u64 v[152:153], s[36:37], 0, v[134:135]
	global_load_dwordx4 v[112:115], v[152:153], off nt
	ds_bpermute_b32 v151, v162, v96
	ds_bpermute_b32 v163, v162, v100
	ds_bpermute_b32 v165, v162, v97
	ds_bpermute_b32 v166, v162, v101
	ds_bpermute_b32 v167, v162, v98
	ds_bpermute_b32 v169, v162, v99
	ds_bpermute_b32 v168, v162, v102
	ds_bpermute_b32 v170, v162, v103
	v_readlane_b32 s54, v252, 20
	v_readlane_b32 s55, v252, 21
	v_readlane_b32 s56, v252, 22
	v_readlane_b32 s57, v252, 23
	v_readlane_b32 s58, v252, 24
	v_readlane_b32 s59, v252, 25
	v_readlane_b32 s60, v252, 26
	v_readlane_b32 s61, v252, 27
	v_readlane_b32 s62, v252, 28
	v_readlane_b32 s63, v252, 29
	v_readlane_b32 s64, v252, 30
	v_readlane_b32 s65, v252, 31
	v_readlane_b32 s66, v252, 32
	v_readlane_b32 s67, v252, 33
	v_readlane_b32 s52, v252, 2
	s_waitcnt lgkmcnt(7)
	v_cndmask_b32_e64 v100, v151, v100, s[0:1]
	s_waitcnt lgkmcnt(6)
	v_cndmask_b32_e64 v164, v96, v163, s[0:1]
	s_waitcnt lgkmcnt(5)
	v_cndmask_b32_e64 v101, v165, v101, s[0:1]
	s_waitcnt lgkmcnt(4)
	v_cndmask_b32_e64 v165, v97, v166, s[0:1]
	s_waitcnt lgkmcnt(3)
	v_cndmask_b32_e64 v96, v167, v102, s[0:1]
	s_waitcnt lgkmcnt(2)
; __device__ __forceinline__ unsigned cvt_pk_bf16(float lo, float hi) { unsigned r; asm volatile("v_cvt_pk_bf16_f32 %0, %1, %2" : "=v"(r) : "v"(lo), "v"(hi)); return r; }
;     __device__ __forceinline__ void operator()(const f32x4 (&acc)[2][2][4][2], const Unit& u, int wr, int wc, int fr, int fq) const {
;     ...
;             for (int m = 0; m < 4; ++m) { const int ra = rowA + ai * HALF + m * 16, rb = rowB + ai * HALF + m * 16; const size_t offA = (size_t)ra * 1024 + col0, offB = (size_t)rb * 1024 + col0;
;                 float ssa = 0.f, ssb = 0.f;
; #pragma unroll
;                 for (int bj = 0; bj < 2; ++bj) {
;                     const f32x4 x0 = acc[ai][bj][m][0], x1 = acc[ai][bj][m][1]; f32x4 za, zb;
; #pragma unroll
;                     for (int e = 0; e < 4; ++e) { const float s1 = __shfl_xor(x1[e], 8), s0 = __shfl_xor(x0[e], 8); za[e] = hi8 ? s1 : x0[e]; zb[e] = hi8 ? x1[e] : s0; }
;                     const f32x4 ba = *(const f32x4*)(base + offA + bj * HALF), bb = *(const f32x4*)(base + offB + bj * HALF);
;                     const f32x4 oa = ba + gs[bj] * za, ob = bb + gs[bj] * zb;
;                     *(f32x4*)(out + offA + bj * HALF) = oa; *(f32x4*)(out + offB + bj * HALF) = ob;
;                     const f32x4 ha = oa * av[bj], hb = ob * av[bj];
;                     *(unsigned long long*)(Hn + offA + bj * HALF) = (unsigned long long)cvt_pk_bf16(ha[0], ha[1]) | ((unsigned long long)cvt_pk_bf16(ha[2], ha[3]) << 32);
;                     *(unsigned long long*)(Hn + offB + bj * HALF) = (unsigned long long)cvt_pk_bf16(hb[0], hb[1]) | ((unsigned long long)cvt_pk_bf16(hb[2], hb[3]) << 32);
;                     ssa += (oa[0] * oa[0] + oa[1] * oa[1]) + (oa[2] * oa[2] + oa[3] * oa[3]); ssb += (ob[0] * ob[0] + ob[1] * ob[1]) + (ob[2] * ob[2] + ob[3] * ob[3]); }
;                 ssa += __shfl_xor(ssa, 8); ssa += __shfl_xor(ssa, 16); ssa += __shfl_xor(ssa, 32);
;                 ssb += __shfl_xor(ssb, 8); ssb += __shfl_xor(ssb, 16); ssb += __shfl_xor(ssb, 32);
;                 if (fq == 0 && hi8 == 0) { atomicAdd(rowss + ra, ssa); atomicAdd(rowss + rb, ssb); } }
	v_cndmask_b32_e64 v97, v169, v103, s[0:1]
	v_readlane_b32 s62, v252, 12
	v_readlane_b32 s63, v252, 13
	v_readlane_b32 s66, v252, 16
	v_readlane_b32 s67, v252, 17
	s_waitcnt lgkmcnt(1)
	v_cndmask_b32_e64 v102, v98, v168, s[0:1]
	s_waitcnt lgkmcnt(0)
	v_cndmask_b32_e64 v103, v99, v170, s[0:1]
	s_mov_b64 s[62:63], s[66:67]
	v_lshl_add_u64 v[116:117], v[116:117], 1, s[4:5]
	v_lshl_add_u64 v[118:119], v[118:119], 1, s[4:5]
	v_lshl_add_u64 v[124:125], s[62:63], 0, v[124:125]
	v_lshl_add_u64 v[134:135], s[62:63], 0, v[134:135]
	ds_bpermute_b32 v163, v162, v94
	ds_bpermute_b32 v151, v162, v89
	v_readlane_b32 s53, v252, 3
	v_readlane_b32 s54, v252, 4
	v_readlane_b32 s55, v252, 5
	v_readlane_b32 s56, v252, 6
	v_readlane_b32 s57, v252, 7
	v_readlane_b32 s58, v252, 8
	v_readlane_b32 s59, v252, 9
	v_readlane_b32 s60, v252, 10
	v_readlane_b32 s61, v252, 11
	v_readlane_b32 s64, v252, 14
	v_readlane_b32 s65, v252, 15
	s_waitcnt vmcnt(1)
	v_pk_fma_f32 v[98:99], v[50:51], v[96:97], v[110:111]
	v_pk_fma_f32 v[96:97], v[48:49], v[100:101], v[108:109]
	s_waitcnt vmcnt(0)
	v_pk_fma_f32 v[102:103], v[50:51], v[102:103], v[114:115]
	v_pk_fma_f32 v[100:101], v[48:49], v[164:165], v[112:113]
	v_pk_mul_f32 v[108:109], v[128:129], v[98:99]
	v_pk_mul_f32 v[110:111], v[130:131], v[96:97]
	global_store_dwordx4 v[124:125], v[96:99], off sc1
	global_store_dwordx4 v[134:135], v[100:103], off sc1
	v_pk_mul_f32 v[112:113], v[128:129], v[102:103]
	v_pk_mul_f32 v[114:115], v[130:131], v[100:101]
	v_cvt_pk_bf16_f32 v110, v110, v111
	v_cvt_pk_bf16_f32 v111, v108, v109
	global_store_dwordx2 v[116:117], v[110:111], off
	v_cvt_pk_bf16_f32 v108, v114, v115
	v_cvt_pk_bf16_f32 v109, v112, v113
	global_store_dwordx2 v[118:119], v[108:109], off
	global_load_dwordx4 v[108:111], v[126:127], off offset:512 nt
	s_nop 0
	global_load_dwordx4 v[112:115], v[152:153], off offset:512 nt
	ds_bpermute_b32 v126, v162, v88
	ds_bpermute_b32 v127, v162, v92
	ds_bpermute_b32 v152, v162, v93
	ds_bpermute_b32 v153, v162, v90
	ds_bpermute_b32 v164, v162, v91
	ds_bpermute_b32 v165, v162, v95
	s_waitcnt lgkmcnt(5)
	v_cndmask_b32_e64 v92, v126, v92, s[0:1]
	s_waitcnt lgkmcnt(4)
	v_cndmask_b32_e64 v126, v88, v127, s[0:1]
	s_waitcnt lgkmcnt(3)
	v_cndmask_b32_e64 v127, v89, v152, s[0:1]
	s_waitcnt lgkmcnt(2)
	v_cndmask_b32_e64 v88, v153, v94, s[0:1]
	v_cndmask_b32_e64 v94, v90, v163, s[0:1]
	s_waitcnt lgkmcnt(1)
	v_cndmask_b32_e64 v89, v164, v95, s[0:1]
	s_waitcnt lgkmcnt(0)
	v_cndmask_b32_e64 v95, v91, v165, s[0:1]
	v_mul_f32_e32 v90, v97, v97
	v_mul_f32_e32 v91, v99, v99
	v_cndmask_b32_e64 v93, v151, v93, s[0:1]
	v_mul_f32_e32 v97, v101, v101
	v_mul_f32_e32 v99, v103, v103
	v_fmac_f32_e32 v90, v96, v96
	v_fmac_f32_e32 v91, v98, v98
	v_fmac_f32_e32 v97, v100, v100
	v_fmac_f32_e32 v99, v102, v102
	v_add_f32_e32 v96, v90, v91
	v_add_f32_e32 v97, v97, v99
	s_waitcnt vmcnt(1)
	v_pk_fma_f32 v[90:91], v[54:55], v[88:89], v[110:111]
	v_pk_fma_f32 v[88:89], v[52:53], v[92:93], v[108:109]
	s_waitcnt vmcnt(0)
	v_pk_fma_f32 v[94:95], v[54:55], v[94:95], v[114:115]
	v_pk_fma_f32 v[92:93], v[52:53], v[126:127], v[112:113]
	v_mul_f32_e32 v98, v89, v89
	v_mul_f32_e32 v99, v91, v91
	v_mul_f32_e32 v100, v93, v93
	v_mul_f32_e32 v101, v95, v95
	v_fmac_f32_e32 v98, v88, v88
	v_fmac_f32_e32 v99, v90, v90
	v_fmac_f32_e32 v100, v92, v92
	v_fmac_f32_e32 v101, v94, v94
	v_add_f32_e32 v98, v98, v99
	v_add_f32_e32 v99, v100, v101
	v_add_f32_e32 v96, v96, v98
	v_add_f32_e32 v97, v97, v99
	ds_bpermute_b32 v98, v162, v96
	ds_bpermute_b32 v99, v162, v97
	global_store_dwordx4 v[124:125], v[88:91], off offset:512 sc1
	global_store_dwordx4 v[134:135], v[92:95], off offset:512 sc1
	s_waitcnt lgkmcnt(1)
	v_add_f32_e32 v98, v96, v98
	s_waitcnt lgkmcnt(0)
	v_add_f32_e32 v99, v97, v99
	ds_bpermute_b32 v100, v133, v98
	ds_bpermute_b32 v101, v133, v99
	v_pk_mul_f32 v[88:89], v[120:121], v[88:89]
	v_pk_mul_f32 v[90:91], v[122:123], v[90:91]
	v_cvt_pk_bf16_f32 v96, v88, v89
	s_waitcnt lgkmcnt(1)
	v_add_f32_e32 v88, v98, v100
	s_waitcnt lgkmcnt(0)
	v_add_f32_e32 v89, v99, v101
	v_cvt_pk_bf16_f32 v97, v90, v91
	ds_bpermute_b32 v90, v132, v88
	ds_bpermute_b32 v91, v132, v89
	v_pk_mul_f32 v[92:93], v[120:121], v[92:93]
	v_pk_mul_f32 v[94:95], v[122:123], v[94:95]
	global_store_dwordx2 v[116:117], v[96:97], off offset:256
	v_cvt_pk_bf16_f32 v92, v92, v93
	v_cvt_pk_bf16_f32 v93, v94, v95
	global_store_dwordx2 v[118:119], v[92:93], off offset:256
	s_and_saveexec_b64 s[28:29], s[18:19]
	s_cbranch_execz .LBB0_549
	v_lshl_add_u64 v[94:95], v[104:105], 2, s[68:69]
	s_waitcnt lgkmcnt(1)
	v_add_f32_e32 v88, v88, v90
	v_lshl_add_u64 v[92:93], v[106:107], 2, s[68:69]
	s_waitcnt lgkmcnt(0)
	v_add_f32_e32 v89, v89, v91
	global_atomic_add_f32 v[94:95], v88, off
	global_atomic_add_f32 v[92:93], v89, off
; __device__ __forceinline__ unsigned cvt_pk_bf16(float lo, float hi) { unsigned r; asm volatile("v_cvt_pk_bf16_f32 %0, %1, %2" : "=v"(r) : "v"(lo), "v"(hi)); return r; }
;     __device__ __forceinline__ void operator()(const f32x4 (&acc)[2][2][4][2], const Unit& u, int wr, int wc, int fr, int fq) const {
;     ...
;             for (int m = 0; m < 4; ++m) { const int ra = rowA + ai * HALF + m * 16, rb = rowB + ai * HALF + m * 16; const size_t offA = (size_t)ra * 1024 + col0, offB = (size_t)rb * 1024 + col0;
;                 float ssa = 0.f, ssb = 0.f;
; #pragma unroll
;                 for (int bj = 0; bj < 2; ++bj) {
;                     const f32x4 x0 = acc[ai][bj][m][0], x1 = acc[ai][bj][m][1]; f32x4 za, zb;
; #pragma unroll
;                     for (int e = 0; e < 4; ++e) { const float s1 = __shfl_xor(x1[e], 8), s0 = __shfl_xor(x0[e], 8); za[e] = hi8 ? s1 : x0[e]; zb[e] = hi8 ? x1[e] : s0; }
;                     const f32x4 ba = *(const f32x4*)(base + offA + bj * HALF), bb = *(const f32x4*)(base + offB + bj * HALF);
;                     const f32x4 oa = ba + gs[bj] * za, ob = bb + gs[bj] * zb;
;                     *(f32x4*)(out + offA + bj * HALF) = oa; *(f32x4*)(out + offB + bj * HALF) = ob;
;                     const f32x4 ha = oa * av[bj], hb = ob * av[bj];
;                     *(unsigned long long*)(Hn + offA + bj * HALF) = (unsigned long long)cvt_pk_bf16(ha[0], ha[1]) | ((unsigned long long)cvt_pk_bf16(ha[2], ha[3]) << 32);
;                     *(unsigned long long*)(Hn + offB + bj * HALF) = (unsigned long long)cvt_pk_bf16(hb[0], hb[1]) | ((unsigned long long)cvt_pk_bf16(hb[2], hb[3]) << 32);
;                     ssa += (oa[0] * oa[0] + oa[1] * oa[1]) + (oa[2] * oa[2] + oa[3] * oa[3]); ssb += (ob[0] * ob[0] + ob[1] * ob[1]) + (ob[2] * ob[2] + ob[3] * ob[3]); }
;                 ssa += __shfl_xor(ssa, 8); ssa += __shfl_xor(ssa, 16); ssa += __shfl_xor(ssa, 32);
;                 ssb += __shfl_xor(ssb, 8); ssb += __shfl_xor(ssb, 16); ssb += __shfl_xor(ssb, 32);
;                 if (fq == 0 && hi8 == 0) { atomicAdd(rowss + ra, ssa); atomicAdd(rowss + rb, ssb); } }
.LBB0_549:
	s_or_b64 exec, exec, s[28:29]
	v_or_b32_e32 v88, 48, v150
	s_waitcnt lgkmcnt(1)
	v_or_b32_e32 v90, 56, v150
	v_ashrrev_i32_e32 v89, 31, v88
	v_lshlrev_b64 v[92:93], 10, v[88:89]
	s_waitcnt lgkmcnt(0)
	v_ashrrev_i32_e32 v91, 31, v90
	v_readlane_b32 s52, v252, 18
	v_lshl_add_u64 v[100:101], v[92:93], 0, v[148:149]
	v_lshlrev_b64 v[92:93], 10, v[90:91]
	v_readlane_b32 s53, v252, 19
	v_lshl_add_u64 v[102:103], v[92:93], 0, v[148:149]
	v_lshlrev_b64 v[104:105], 2, v[100:101]
	s_mov_b64 s[36:37], s[52:53]
	v_lshl_add_u64 v[106:107], s[36:37], 0, v[104:105]
	v_lshlrev_b64 v[108:109], 2, v[102:103]
	global_load_dwordx4 v[92:95], v[106:107], off nt
	v_lshl_add_u64 v[110:111], s[36:37], 0, v[108:109]
	global_load_dwordx4 v[96:99], v[110:111], off nt
	ds_bpermute_b32 v112, v162, v80
	ds_bpermute_b32 v113, v162, v84
	ds_bpermute_b32 v114, v162, v81
	ds_bpermute_b32 v115, v162, v85
	ds_bpermute_b32 v116, v162, v82
	ds_bpermute_b32 v118, v162, v83
	ds_bpermute_b32 v117, v162, v86
	ds_bpermute_b32 v119, v162, v87
	v_readlane_b32 s54, v252, 20
	v_readlane_b32 s55, v252, 21
	v_readlane_b32 s56, v252, 22
	v_readlane_b32 s57, v252, 23
	v_readlane_b32 s58, v252, 24
	v_readlane_b32 s59, v252, 25
	v_readlane_b32 s60, v252, 26
	v_readlane_b32 s61, v252, 27
	v_readlane_b32 s62, v252, 28
	v_readlane_b32 s63, v252, 29
	v_readlane_b32 s64, v252, 30
	v_readlane_b32 s65, v252, 31
	v_readlane_b32 s66, v252, 32
	v_readlane_b32 s67, v252, 33
	v_readlane_b32 s52, v252, 2
	s_waitcnt lgkmcnt(7)
	v_cndmask_b32_e64 v84, v112, v84, s[0:1]
	s_waitcnt lgkmcnt(6)
	v_cndmask_b32_e64 v112, v80, v113, s[0:1]
	s_waitcnt lgkmcnt(5)
	v_cndmask_b32_e64 v85, v114, v85, s[0:1]
	s_waitcnt lgkmcnt(4)
	v_cndmask_b32_e64 v113, v81, v115, s[0:1]
	s_waitcnt lgkmcnt(3)
	v_cndmask_b32_e64 v80, v116, v86, s[0:1]
	s_waitcnt lgkmcnt(2)
	v_cndmask_b32_e64 v81, v118, v87, s[0:1]
	v_readlane_b32 s62, v252, 12
	v_readlane_b32 s63, v252, 13
	v_readlane_b32 s66, v252, 16
	v_readlane_b32 s67, v252, 17
	s_waitcnt lgkmcnt(1)
	v_cndmask_b32_e64 v86, v82, v117, s[0:1]
	s_waitcnt lgkmcnt(0)
	v_cndmask_b32_e64 v87, v83, v119, s[0:1]
	s_mov_b64 s[62:63], s[66:67]
	v_lshl_add_u64 v[100:101], v[100:101], 1, s[4:5]
	v_lshl_add_u64 v[102:103], v[102:103], 1, s[4:5]
	v_lshl_add_u64 v[104:105], s[62:63], 0, v[104:105]
	v_lshl_add_u64 v[108:109], s[62:63], 0, v[108:109]
	ds_bpermute_b32 v114, v162, v75
	ds_bpermute_b32 v115, v162, v79
	v_readlane_b32 s53, v252, 3
	v_readlane_b32 s54, v252, 4
	v_readlane_b32 s55, v252, 5
	v_readlane_b32 s56, v252, 6
	v_readlane_b32 s57, v252, 7
	v_readlane_b32 s58, v252, 8
	v_readlane_b32 s59, v252, 9
	v_readlane_b32 s60, v252, 10
	v_readlane_b32 s61, v252, 11
	v_readlane_b32 s64, v252, 14
	v_readlane_b32 s65, v252, 15
	s_waitcnt vmcnt(1)
	v_pk_fma_f32 v[82:83], v[50:51], v[80:81], v[94:95]
	v_pk_fma_f32 v[80:81], v[48:49], v[84:85], v[92:93]
	s_waitcnt vmcnt(0)
	v_pk_fma_f32 v[86:87], v[50:51], v[86:87], v[98:99]
	v_pk_fma_f32 v[84:85], v[48:49], v[112:113], v[96:97]
	v_pk_mul_f32 v[92:93], v[128:129], v[82:83]
	v_pk_mul_f32 v[94:95], v[130:131], v[80:81]
	global_store_dwordx4 v[104:105], v[80:83], off sc1
	global_store_dwordx4 v[108:109], v[84:87], off sc1
	v_pk_mul_f32 v[96:97], v[128:129], v[86:87]
	v_pk_mul_f32 v[98:99], v[130:131], v[84:85]
	v_cvt_pk_bf16_f32 v94, v94, v95
	v_cvt_pk_bf16_f32 v95, v92, v93
	global_store_dwordx2 v[100:101], v[94:95], off
	v_cvt_pk_bf16_f32 v92, v98, v99
	v_cvt_pk_bf16_f32 v93, v96, v97
	global_store_dwordx2 v[102:103], v[92:93], off
	global_load_dwordx4 v[92:95], v[106:107], off offset:512 nt
	s_nop 0
	global_load_dwordx4 v[96:99], v[110:111], off offset:512 nt
	ds_bpermute_b32 v106, v162, v72
	ds_bpermute_b32 v107, v162, v76
	ds_bpermute_b32 v111, v162, v77
	ds_bpermute_b32 v112, v162, v74
	ds_bpermute_b32 v113, v162, v78
	ds_bpermute_b32 v110, v162, v73
	s_waitcnt lgkmcnt(5)
	v_cndmask_b32_e64 v76, v106, v76, s[0:1]
	s_waitcnt lgkmcnt(4)
	v_cndmask_b32_e64 v106, v72, v107, s[0:1]
	s_waitcnt lgkmcnt(3)
	v_cndmask_b32_e64 v107, v73, v111, s[0:1]
	s_waitcnt lgkmcnt(2)
	v_cndmask_b32_e64 v72, v112, v78, s[0:1]
	s_waitcnt lgkmcnt(1)
	v_cndmask_b32_e64 v78, v74, v113, s[0:1]
	v_cndmask_b32_e64 v73, v114, v79, s[0:1]
	v_cndmask_b32_e64 v79, v75, v115, s[0:1]
	v_mul_f32_e32 v74, v81, v81
	v_mul_f32_e32 v75, v83, v83
	s_waitcnt lgkmcnt(0)
	v_cndmask_b32_e64 v77, v110, v77, s[0:1]
	v_mul_f32_e32 v81, v85, v85
	v_mul_f32_e32 v83, v87, v87
	v_fmac_f32_e32 v74, v80, v80
	v_fmac_f32_e32 v75, v82, v82
	v_fmac_f32_e32 v81, v84, v84
	v_fmac_f32_e32 v83, v86, v86
	v_add_f32_e32 v80, v74, v75
	v_add_f32_e32 v81, v81, v83
	s_waitcnt vmcnt(1)
	v_pk_fma_f32 v[74:75], v[54:55], v[72:73], v[94:95]
	v_pk_fma_f32 v[72:73], v[52:53], v[76:77], v[92:93]
	s_waitcnt vmcnt(0)
	v_pk_fma_f32 v[78:79], v[54:55], v[78:79], v[98:99]
	v_pk_fma_f32 v[76:77], v[52:53], v[106:107], v[96:97]
	v_mul_f32_e32 v82, v73, v73
	v_mul_f32_e32 v83, v75, v75
	v_mul_f32_e32 v84, v77, v77
	v_mul_f32_e32 v85, v79, v79
	v_fmac_f32_e32 v82, v72, v72
	v_fmac_f32_e32 v83, v74, v74
	v_fmac_f32_e32 v84, v76, v76
	v_fmac_f32_e32 v85, v78, v78
	v_add_f32_e32 v82, v82, v83
	v_add_f32_e32 v83, v84, v85
	v_add_f32_e32 v80, v80, v82
	v_add_f32_e32 v81, v81, v83
	ds_bpermute_b32 v82, v162, v80
	ds_bpermute_b32 v83, v162, v81
	global_store_dwordx4 v[104:105], v[72:75], off offset:512 sc1
	global_store_dwordx4 v[108:109], v[76:79], off offset:512 sc1
	s_waitcnt lgkmcnt(1)
	v_add_f32_e32 v82, v80, v82
	s_waitcnt lgkmcnt(0)
	v_add_f32_e32 v83, v81, v83
	ds_bpermute_b32 v84, v133, v82
	ds_bpermute_b32 v85, v133, v83
	v_pk_mul_f32 v[72:73], v[120:121], v[72:73]
	v_pk_mul_f32 v[74:75], v[122:123], v[74:75]
	v_cvt_pk_bf16_f32 v80, v72, v73
	s_waitcnt lgkmcnt(1)
	v_add_f32_e32 v72, v82, v84
	s_waitcnt lgkmcnt(0)
	v_add_f32_e32 v73, v83, v85
	v_cvt_pk_bf16_f32 v81, v74, v75
	ds_bpermute_b32 v74, v132, v72
	ds_bpermute_b32 v75, v132, v73
	v_pk_mul_f32 v[76:77], v[120:121], v[76:77]
	v_pk_mul_f32 v[78:79], v[122:123], v[78:79]
	global_store_dwordx2 v[100:101], v[80:81], off offset:256
	v_cvt_pk_bf16_f32 v76, v76, v77
	v_cvt_pk_bf16_f32 v77, v78, v79
	global_store_dwordx2 v[102:103], v[76:77], off offset:256
	s_and_saveexec_b64 s[28:29], s[18:19]
	s_cbranch_execz .LBB0_551
	v_lshl_add_u64 v[78:79], v[88:89], 2, s[68:69]
	s_waitcnt lgkmcnt(1)
	v_add_f32_e32 v72, v72, v74
	v_lshl_add_u64 v[76:77], v[90:91], 2, s[68:69]
	s_waitcnt lgkmcnt(0)
	v_add_f32_e32 v73, v73, v75
	global_atomic_add_f32 v[78:79], v72, off
	global_atomic_add_f32 v[76:77], v73, off
; __device__ __forceinline__ unsigned cvt_pk_bf16(float lo, float hi) { unsigned r; asm volatile("v_cvt_pk_bf16_f32 %0, %1, %2" : "=v"(r) : "v"(lo), "v"(hi)); return r; }
;     __device__ __forceinline__ void operator()(const f32x4 (&acc)[2][2][4][2], const Unit& u, int wr, int wc, int fr, int fq) const {
;     ...
;             for (int m = 0; m < 4; ++m) { const int ra = rowA + ai * HALF + m * 16, rb = rowB + ai * HALF + m * 16; const size_t offA = (size_t)ra * 1024 + col0, offB = (size_t)rb * 1024 + col0;
;                 float ssa = 0.f, ssb = 0.f;
; #pragma unroll
;                 for (int bj = 0; bj < 2; ++bj) {
;                     const f32x4 x0 = acc[ai][bj][m][0], x1 = acc[ai][bj][m][1]; f32x4 za, zb;
; #pragma unroll
;                     for (int e = 0; e < 4; ++e) { const float s1 = __shfl_xor(x1[e], 8), s0 = __shfl_xor(x0[e], 8); za[e] = hi8 ? s1 : x0[e]; zb[e] = hi8 ? x1[e] : s0; }
;                     const f32x4 ba = *(const f32x4*)(base + offA + bj * HALF), bb = *(const f32x4*)(base + offB + bj * HALF);
;                     const f32x4 oa = ba + gs[bj] * za, ob = bb + gs[bj] * zb;
;                     *(f32x4*)(out + offA + bj * HALF) = oa; *(f32x4*)(out + offB + bj * HALF) = ob;
;                     const f32x4 ha = oa * av[bj], hb = ob * av[bj];
;                     *(unsigned long long*)(Hn + offA + bj * HALF) = (unsigned long long)cvt_pk_bf16(ha[0], ha[1]) | ((unsigned long long)cvt_pk_bf16(ha[2], ha[3]) << 32);
;                     *(unsigned long long*)(Hn + offB + bj * HALF) = (unsigned long long)cvt_pk_bf16(hb[0], hb[1]) | ((unsigned long long)cvt_pk_bf16(hb[2], hb[3]) << 32);
;                     ssa += (oa[0] * oa[0] + oa[1] * oa[1]) + (oa[2] * oa[2] + oa[3] * oa[3]); ssb += (ob[0] * ob[0] + ob[1] * ob[1]) + (ob[2] * ob[2] + ob[3] * ob[3]); }
;                 ssa += __shfl_xor(ssa, 8); ssa += __shfl_xor(ssa, 16); ssa += __shfl_xor(ssa, 32);
;                 ssb += __shfl_xor(ssb, 8); ssb += __shfl_xor(ssb, 16); ssb += __shfl_xor(ssb, 32);
;                 if (fq == 0 && hi8 == 0) { atomicAdd(rowss + ra, ssa); atomicAdd(rowss + rb, ssb); } }
.LBB0_551:
	s_or_b64 exec, exec, s[28:29]
	v_add_u32_e32 v72, 0x80, v150
	s_waitcnt lgkmcnt(1)
	v_add_u32_e32 v74, 0x88, v150
	v_ashrrev_i32_e32 v73, 31, v72
	v_lshlrev_b64 v[76:77], 10, v[72:73]
	s_waitcnt lgkmcnt(0)
	v_ashrrev_i32_e32 v75, 31, v74
	v_readlane_b32 s52, v252, 18
	v_lshl_add_u64 v[84:85], v[76:77], 0, v[148:149]
	v_lshlrev_b64 v[76:77], 10, v[74:75]
	v_readlane_b32 s53, v252, 19
	v_lshl_add_u64 v[86:87], v[76:77], 0, v[148:149]
	v_lshlrev_b64 v[88:89], 2, v[84:85]
	s_mov_b64 s[36:37], s[52:53]
	v_lshl_add_u64 v[90:91], s[36:37], 0, v[88:89]
	v_lshlrev_b64 v[92:93], 2, v[86:87]
	global_load_dwordx4 v[76:79], v[90:91], off nt
	v_lshl_add_u64 v[94:95], s[36:37], 0, v[92:93]
	global_load_dwordx4 v[80:83], v[94:95], off nt
	ds_bpermute_b32 v96, v162, v64
	ds_bpermute_b32 v97, v162, v68
	ds_bpermute_b32 v98, v162, v65
	ds_bpermute_b32 v99, v162, v69
	ds_bpermute_b32 v100, v162, v66
	ds_bpermute_b32 v102, v162, v67
	ds_bpermute_b32 v101, v162, v70
	ds_bpermute_b32 v103, v162, v71
	v_readlane_b32 s54, v252, 20
	v_readlane_b32 s55, v252, 21
	v_readlane_b32 s56, v252, 22
	v_readlane_b32 s57, v252, 23
	v_readlane_b32 s58, v252, 24
	v_readlane_b32 s59, v252, 25
	v_readlane_b32 s60, v252, 26
	v_readlane_b32 s61, v252, 27
	v_readlane_b32 s62, v252, 28
	v_readlane_b32 s63, v252, 29
	v_readlane_b32 s64, v252, 30
	v_readlane_b32 s65, v252, 31
	v_readlane_b32 s66, v252, 32
	v_readlane_b32 s67, v252, 33
	v_readlane_b32 s52, v252, 2
	s_waitcnt lgkmcnt(7)
	v_cndmask_b32_e64 v68, v96, v68, s[0:1]
	s_waitcnt lgkmcnt(6)
	v_cndmask_b32_e64 v96, v64, v97, s[0:1]
	s_waitcnt lgkmcnt(5)
	v_cndmask_b32_e64 v69, v98, v69, s[0:1]
	s_waitcnt lgkmcnt(4)
	v_cndmask_b32_e64 v97, v65, v99, s[0:1]
	s_waitcnt lgkmcnt(3)
	v_cndmask_b32_e64 v64, v100, v70, s[0:1]
	s_waitcnt lgkmcnt(2)
	v_cndmask_b32_e64 v65, v102, v71, s[0:1]
	v_readlane_b32 s62, v252, 12
	v_readlane_b32 s63, v252, 13
	v_readlane_b32 s66, v252, 16
	v_readlane_b32 s67, v252, 17
	s_waitcnt lgkmcnt(1)
	v_cndmask_b32_e64 v70, v66, v101, s[0:1]
	s_waitcnt lgkmcnt(0)
	v_cndmask_b32_e64 v71, v67, v103, s[0:1]
	s_mov_b64 s[62:63], s[66:67]
	v_lshl_add_u64 v[84:85], v[84:85], 1, s[4:5]
	v_lshl_add_u64 v[86:87], v[86:87], 1, s[4:5]
	v_lshl_add_u64 v[88:89], s[62:63], 0, v[88:89]
	v_lshl_add_u64 v[92:93], s[62:63], 0, v[92:93]
	ds_bpermute_b32 v98, v162, v59
	ds_bpermute_b32 v99, v162, v63
	v_readlane_b32 s53, v252, 3
	v_readlane_b32 s54, v252, 4
	v_readlane_b32 s55, v252, 5
	v_readlane_b32 s56, v252, 6
	v_readlane_b32 s57, v252, 7
	v_readlane_b32 s58, v252, 8
	v_readlane_b32 s59, v252, 9
	v_readlane_b32 s60, v252, 10
	v_readlane_b32 s61, v252, 11
	v_readlane_b32 s64, v252, 14
	v_readlane_b32 s65, v252, 15
	s_waitcnt vmcnt(1)
	v_pk_fma_f32 v[66:67], v[50:51], v[64:65], v[78:79]
	v_pk_fma_f32 v[64:65], v[48:49], v[68:69], v[76:77]
	s_waitcnt vmcnt(0)
	v_pk_fma_f32 v[70:71], v[50:51], v[70:71], v[82:83]
	v_pk_fma_f32 v[68:69], v[48:49], v[96:97], v[80:81]
	v_pk_mul_f32 v[76:77], v[128:129], v[66:67]
	v_pk_mul_f32 v[78:79], v[130:131], v[64:65]
	global_store_dwordx4 v[88:89], v[64:67], off sc1
	global_store_dwordx4 v[92:93], v[68:71], off sc1
	v_pk_mul_f32 v[80:81], v[128:129], v[70:71]
	v_pk_mul_f32 v[82:83], v[130:131], v[68:69]
	v_cvt_pk_bf16_f32 v78, v78, v79
	v_cvt_pk_bf16_f32 v79, v76, v77
	global_store_dwordx2 v[84:85], v[78:79], off
	v_cvt_pk_bf16_f32 v76, v82, v83
	v_cvt_pk_bf16_f32 v77, v80, v81
	global_store_dwordx2 v[86:87], v[76:77], off
	global_load_dwordx4 v[76:79], v[90:91], off offset:512 nt
	s_nop 0
	global_load_dwordx4 v[80:83], v[94:95], off offset:512 nt
	ds_bpermute_b32 v90, v162, v56
	ds_bpermute_b32 v91, v162, v60
	ds_bpermute_b32 v95, v162, v61
	ds_bpermute_b32 v96, v162, v58
	ds_bpermute_b32 v97, v162, v62
	ds_bpermute_b32 v94, v162, v57
	s_waitcnt lgkmcnt(5)
	v_cndmask_b32_e64 v60, v90, v60, s[0:1]
	s_waitcnt lgkmcnt(4)
	v_cndmask_b32_e64 v90, v56, v91, s[0:1]
	s_waitcnt lgkmcnt(3)
	v_cndmask_b32_e64 v91, v57, v95, s[0:1]
	s_waitcnt lgkmcnt(2)
	v_cndmask_b32_e64 v56, v96, v62, s[0:1]
	s_waitcnt lgkmcnt(1)
	v_cndmask_b32_e64 v62, v58, v97, s[0:1]
	v_cndmask_b32_e64 v57, v98, v63, s[0:1]
	v_cndmask_b32_e64 v63, v59, v99, s[0:1]
	v_mul_f32_e32 v58, v65, v65
	v_mul_f32_e32 v59, v67, v67
	s_waitcnt lgkmcnt(0)
	v_cndmask_b32_e64 v61, v94, v61, s[0:1]
	v_mul_f32_e32 v65, v69, v69
	v_mul_f32_e32 v67, v71, v71
	v_fmac_f32_e32 v58, v64, v64
	v_fmac_f32_e32 v59, v66, v66
	v_fmac_f32_e32 v65, v68, v68
	v_fmac_f32_e32 v67, v70, v70
	v_add_f32_e32 v64, v58, v59
	v_add_f32_e32 v65, v65, v67
	s_waitcnt vmcnt(1)
	v_pk_fma_f32 v[58:59], v[54:55], v[56:57], v[78:79]
	v_pk_fma_f32 v[56:57], v[52:53], v[60:61], v[76:77]
	s_waitcnt vmcnt(0)
	v_pk_fma_f32 v[62:63], v[54:55], v[62:63], v[82:83]
	v_pk_fma_f32 v[60:61], v[52:53], v[90:91], v[80:81]
	v_mul_f32_e32 v66, v57, v57
	v_mul_f32_e32 v67, v59, v59
	v_mul_f32_e32 v68, v61, v61
	v_mul_f32_e32 v69, v63, v63
	v_fmac_f32_e32 v66, v56, v56
	v_fmac_f32_e32 v67, v58, v58
	v_fmac_f32_e32 v68, v60, v60
	v_fmac_f32_e32 v69, v62, v62
	v_add_f32_e32 v66, v66, v67
	v_add_f32_e32 v67, v68, v69
	v_add_f32_e32 v64, v64, v66
	v_add_f32_e32 v65, v65, v67
	ds_bpermute_b32 v66, v162, v64
	ds_bpermute_b32 v67, v162, v65
	global_store_dwordx4 v[88:89], v[56:59], off offset:512 sc1
	global_store_dwordx4 v[92:93], v[60:63], off offset:512 sc1
	s_waitcnt lgkmcnt(1)
	v_add_f32_e32 v66, v64, v66
	s_waitcnt lgkmcnt(0)
	v_add_f32_e32 v67, v65, v67
	ds_bpermute_b32 v68, v133, v66
	ds_bpermute_b32 v69, v133, v67
	v_pk_mul_f32 v[56:57], v[120:121], v[56:57]
	v_pk_mul_f32 v[58:59], v[122:123], v[58:59]
	v_cvt_pk_bf16_f32 v64, v56, v57
	s_waitcnt lgkmcnt(1)
	v_add_f32_e32 v56, v66, v68
	s_waitcnt lgkmcnt(0)
	v_add_f32_e32 v57, v67, v69
	v_cvt_pk_bf16_f32 v65, v58, v59
	ds_bpermute_b32 v58, v132, v56
	ds_bpermute_b32 v59, v132, v57
	v_pk_mul_f32 v[60:61], v[120:121], v[60:61]
	v_pk_mul_f32 v[62:63], v[122:123], v[62:63]
	global_store_dwordx2 v[84:85], v[64:65], off offset:256
	v_cvt_pk_bf16_f32 v60, v60, v61
	v_cvt_pk_bf16_f32 v61, v62, v63
	global_store_dwordx2 v[86:87], v[60:61], off offset:256
	s_and_saveexec_b64 s[28:29], s[18:19]
	s_cbranch_execz .LBB0_553
	v_lshl_add_u64 v[62:63], v[72:73], 2, s[68:69]
	s_waitcnt lgkmcnt(1)
	v_add_f32_e32 v56, v56, v58
	v_lshl_add_u64 v[60:61], v[74:75], 2, s[68:69]
	s_waitcnt lgkmcnt(0)
	v_add_f32_e32 v57, v57, v59
	global_atomic_add_f32 v[62:63], v56, off
	global_atomic_add_f32 v[60:61], v57, off
; __device__ __forceinline__ unsigned cvt_pk_bf16(float lo, float hi) { unsigned r; asm volatile("v_cvt_pk_bf16_f32 %0, %1, %2" : "=v"(r) : "v"(lo), "v"(hi)); return r; }
;     __device__ __forceinline__ void operator()(const f32x4 (&acc)[2][2][4][2], const Unit& u, int wr, int wc, int fr, int fq) const {
;     ...
;             for (int m = 0; m < 4; ++m) { const int ra = rowA + ai * HALF + m * 16, rb = rowB + ai * HALF + m * 16; const size_t offA = (size_t)ra * 1024 + col0, offB = (size_t)rb * 1024 + col0;
;                 float ssa = 0.f, ssb = 0.f;
; #pragma unroll
;                 for (int bj = 0; bj < 2; ++bj) {
;                     const f32x4 x0 = acc[ai][bj][m][0], x1 = acc[ai][bj][m][1]; f32x4 za, zb;
; #pragma unroll
;                     for (int e = 0; e < 4; ++e) { const float s1 = __shfl_xor(x1[e], 8), s0 = __shfl_xor(x0[e], 8); za[e] = hi8 ? s1 : x0[e]; zb[e] = hi8 ? x1[e] : s0; }
;                     const f32x4 ba = *(const f32x4*)(base + offA + bj * HALF), bb = *(const f32x4*)(base + offB + bj * HALF);
;                     const f32x4 oa = ba + gs[bj] * za, ob = bb + gs[bj] * zb;
;                     *(f32x4*)(out + offA + bj * HALF) = oa; *(f32x4*)(out + offB + bj * HALF) = ob;
;                     const f32x4 ha = oa * av[bj], hb = ob * av[bj];
;                     *(unsigned long long*)(Hn + offA + bj * HALF) = (unsigned long long)cvt_pk_bf16(ha[0], ha[1]) | ((unsigned long long)cvt_pk_bf16(ha[2], ha[3]) << 32);
;                     *(unsigned long long*)(Hn + offB + bj * HALF) = (unsigned long long)cvt_pk_bf16(hb[0], hb[1]) | ((unsigned long long)cvt_pk_bf16(hb[2], hb[3]) << 32);
;                     ssa += (oa[0] * oa[0] + oa[1] * oa[1]) + (oa[2] * oa[2] + oa[3] * oa[3]); ssb += (ob[0] * ob[0] + ob[1] * ob[1]) + (ob[2] * ob[2] + ob[3] * ob[3]); }
;                 ssa += __shfl_xor(ssa, 8); ssa += __shfl_xor(ssa, 16); ssa += __shfl_xor(ssa, 32);
;                 ssb += __shfl_xor(ssb, 8); ssb += __shfl_xor(ssb, 16); ssb += __shfl_xor(ssb, 32);
;                 if (fq == 0 && hi8 == 0) { atomicAdd(rowss + ra, ssa); atomicAdd(rowss + rb, ssb); } }
.LBB0_553:
	s_or_b64 exec, exec, s[28:29]
	v_add_u32_e32 v56, 0x90, v150
	s_waitcnt lgkmcnt(1)
	v_add_u32_e32 v58, 0x98, v150
	v_ashrrev_i32_e32 v57, 31, v56
	v_lshlrev_b64 v[60:61], 10, v[56:57]
	s_waitcnt lgkmcnt(0)
	v_ashrrev_i32_e32 v59, 31, v58
	v_readlane_b32 s52, v252, 18
	v_lshl_add_u64 v[68:69], v[60:61], 0, v[148:149]
	v_lshlrev_b64 v[60:61], 10, v[58:59]
	v_readlane_b32 s53, v252, 19
	v_lshl_add_u64 v[70:71], v[60:61], 0, v[148:149]
	v_lshlrev_b64 v[72:73], 2, v[68:69]
	s_mov_b64 s[36:37], s[52:53]
	v_lshl_add_u64 v[74:75], s[36:37], 0, v[72:73]
	v_lshlrev_b64 v[76:77], 2, v[70:71]
	global_load_dwordx4 v[60:63], v[74:75], off nt
	v_lshl_add_u64 v[78:79], s[36:37], 0, v[76:77]
	global_load_dwordx4 v[64:67], v[78:79], off nt
	ds_bpermute_b32 v80, v162, v40
	ds_bpermute_b32 v81, v162, v44
	ds_bpermute_b32 v82, v162, v41
	ds_bpermute_b32 v83, v162, v45
	ds_bpermute_b32 v84, v162, v42
	ds_bpermute_b32 v86, v162, v43
	ds_bpermute_b32 v85, v162, v46
	ds_bpermute_b32 v87, v162, v47
	v_readlane_b32 s54, v252, 20
	v_readlane_b32 s55, v252, 21
	v_readlane_b32 s56, v252, 22
	v_readlane_b32 s57, v252, 23
	v_readlane_b32 s58, v252, 24
	v_readlane_b32 s59, v252, 25
	v_readlane_b32 s60, v252, 26
	v_readlane_b32 s61, v252, 27
	v_readlane_b32 s62, v252, 28
	v_readlane_b32 s63, v252, 29
	v_readlane_b32 s64, v252, 30
	v_readlane_b32 s65, v252, 31
	v_readlane_b32 s66, v252, 32
	v_readlane_b32 s67, v252, 33
	v_readlane_b32 s52, v252, 2
	s_waitcnt lgkmcnt(7)
	v_cndmask_b32_e64 v44, v80, v44, s[0:1]
	s_waitcnt lgkmcnt(6)
	v_cndmask_b32_e64 v80, v40, v81, s[0:1]
	s_waitcnt lgkmcnt(5)
	v_cndmask_b32_e64 v45, v82, v45, s[0:1]
	s_waitcnt lgkmcnt(4)
	v_cndmask_b32_e64 v81, v41, v83, s[0:1]
	s_waitcnt lgkmcnt(3)
	v_cndmask_b32_e64 v40, v84, v46, s[0:1]
	s_waitcnt lgkmcnt(2)
	v_cndmask_b32_e64 v41, v86, v47, s[0:1]
	v_readlane_b32 s62, v252, 12
	v_readlane_b32 s63, v252, 13
	v_readlane_b32 s66, v252, 16
	v_readlane_b32 s67, v252, 17
	s_waitcnt lgkmcnt(1)
	v_cndmask_b32_e64 v46, v42, v85, s[0:1]
	s_waitcnt lgkmcnt(0)
	v_cndmask_b32_e64 v47, v43, v87, s[0:1]
	s_mov_b64 s[62:63], s[66:67]
	v_lshl_add_u64 v[68:69], v[68:69], 1, s[4:5]
	v_lshl_add_u64 v[70:71], v[70:71], 1, s[4:5]
	v_lshl_add_u64 v[72:73], s[62:63], 0, v[72:73]
	v_lshl_add_u64 v[76:77], s[62:63], 0, v[76:77]
	ds_bpermute_b32 v82, v162, v35
	ds_bpermute_b32 v83, v162, v39
	v_readlane_b32 s53, v252, 3
	v_readlane_b32 s54, v252, 4
	v_readlane_b32 s55, v252, 5
	v_readlane_b32 s56, v252, 6
	v_readlane_b32 s57, v252, 7
	v_readlane_b32 s58, v252, 8
	v_readlane_b32 s59, v252, 9
	v_readlane_b32 s60, v252, 10
	v_readlane_b32 s61, v252, 11
	v_readlane_b32 s64, v252, 14
	v_readlane_b32 s65, v252, 15
	s_waitcnt vmcnt(1)
	v_pk_fma_f32 v[42:43], v[50:51], v[40:41], v[62:63]
	v_pk_fma_f32 v[40:41], v[48:49], v[44:45], v[60:61]
	s_waitcnt vmcnt(0)
	v_pk_fma_f32 v[46:47], v[50:51], v[46:47], v[66:67]
	v_pk_fma_f32 v[44:45], v[48:49], v[80:81], v[64:65]
	v_pk_mul_f32 v[60:61], v[128:129], v[42:43]
	v_pk_mul_f32 v[62:63], v[130:131], v[40:41]
	global_store_dwordx4 v[72:73], v[40:43], off sc1
	global_store_dwordx4 v[76:77], v[44:47], off sc1
	v_pk_mul_f32 v[64:65], v[128:129], v[46:47]
	v_pk_mul_f32 v[66:67], v[130:131], v[44:45]
	v_cvt_pk_bf16_f32 v62, v62, v63
	v_cvt_pk_bf16_f32 v63, v60, v61
	global_store_dwordx2 v[68:69], v[62:63], off
	v_cvt_pk_bf16_f32 v60, v66, v67
	v_cvt_pk_bf16_f32 v61, v64, v65
	global_store_dwordx2 v[70:71], v[60:61], off
	global_load_dwordx4 v[60:63], v[74:75], off offset:512 nt
	s_nop 0
	global_load_dwordx4 v[64:67], v[78:79], off offset:512 nt
	ds_bpermute_b32 v74, v162, v32
	ds_bpermute_b32 v75, v162, v36
	ds_bpermute_b32 v79, v162, v37
	ds_bpermute_b32 v80, v162, v34
	ds_bpermute_b32 v81, v162, v38
	ds_bpermute_b32 v78, v162, v33
	s_waitcnt lgkmcnt(5)
	v_cndmask_b32_e64 v36, v74, v36, s[0:1]
	s_waitcnt lgkmcnt(4)
	v_cndmask_b32_e64 v74, v32, v75, s[0:1]
	s_waitcnt lgkmcnt(3)
	v_cndmask_b32_e64 v75, v33, v79, s[0:1]
	s_waitcnt lgkmcnt(2)
	v_cndmask_b32_e64 v32, v80, v38, s[0:1]
	s_waitcnt lgkmcnt(1)
	v_cndmask_b32_e64 v38, v34, v81, s[0:1]
	v_cndmask_b32_e64 v33, v82, v39, s[0:1]
	v_cndmask_b32_e64 v39, v35, v83, s[0:1]
	v_mul_f32_e32 v34, v41, v41
	v_mul_f32_e32 v35, v43, v43
	s_waitcnt lgkmcnt(0)
	v_cndmask_b32_e64 v37, v78, v37, s[0:1]
	v_mul_f32_e32 v41, v45, v45
	v_mul_f32_e32 v43, v47, v47
	v_fmac_f32_e32 v34, v40, v40
	v_fmac_f32_e32 v35, v42, v42
	v_fmac_f32_e32 v41, v44, v44
	v_fmac_f32_e32 v43, v46, v46
	v_add_f32_e32 v40, v34, v35
	v_add_f32_e32 v41, v41, v43
	s_waitcnt vmcnt(1)
	v_pk_fma_f32 v[34:35], v[54:55], v[32:33], v[62:63]
	v_pk_fma_f32 v[32:33], v[52:53], v[36:37], v[60:61]
	s_waitcnt vmcnt(0)
	v_pk_fma_f32 v[38:39], v[54:55], v[38:39], v[66:67]
	v_pk_fma_f32 v[36:37], v[52:53], v[74:75], v[64:65]
	v_mul_f32_e32 v42, v33, v33
	v_mul_f32_e32 v43, v35, v35
	v_mul_f32_e32 v44, v37, v37
	v_mul_f32_e32 v45, v39, v39
	v_fmac_f32_e32 v42, v32, v32
	v_fmac_f32_e32 v43, v34, v34
	v_fmac_f32_e32 v44, v36, v36
	v_fmac_f32_e32 v45, v38, v38
	v_add_f32_e32 v42, v42, v43
	v_add_f32_e32 v43, v44, v45
	v_add_f32_e32 v40, v40, v42
	v_add_f32_e32 v41, v41, v43
	ds_bpermute_b32 v42, v162, v40
	ds_bpermute_b32 v43, v162, v41
	global_store_dwordx4 v[72:73], v[32:35], off offset:512 sc1
	global_store_dwordx4 v[76:77], v[36:39], off offset:512 sc1
	s_waitcnt lgkmcnt(1)
	v_add_f32_e32 v42, v40, v42
	s_waitcnt lgkmcnt(0)
	v_add_f32_e32 v43, v41, v43
	ds_bpermute_b32 v44, v133, v42
	ds_bpermute_b32 v45, v133, v43
	v_pk_mul_f32 v[32:33], v[120:121], v[32:33]
	v_pk_mul_f32 v[34:35], v[122:123], v[34:35]
	v_cvt_pk_bf16_f32 v40, v32, v33
	s_waitcnt lgkmcnt(1)
	v_add_f32_e32 v32, v42, v44
	s_waitcnt lgkmcnt(0)
	v_add_f32_e32 v33, v43, v45
	v_cvt_pk_bf16_f32 v41, v34, v35
	ds_bpermute_b32 v34, v132, v32
	ds_bpermute_b32 v35, v132, v33
	v_pk_mul_f32 v[36:37], v[120:121], v[36:37]
	v_pk_mul_f32 v[38:39], v[122:123], v[38:39]
	global_store_dwordx2 v[68:69], v[40:41], off offset:256
	v_cvt_pk_bf16_f32 v36, v36, v37
	v_cvt_pk_bf16_f32 v37, v38, v39
	global_store_dwordx2 v[70:71], v[36:37], off offset:256
	s_and_saveexec_b64 s[28:29], s[18:19]
	s_cbranch_execz .LBB0_555
	v_lshl_add_u64 v[38:39], v[56:57], 2, s[68:69]
	s_waitcnt lgkmcnt(1)
	v_add_f32_e32 v32, v32, v34
	v_lshl_add_u64 v[36:37], v[58:59], 2, s[68:69]
	s_waitcnt lgkmcnt(0)
	v_add_f32_e32 v33, v33, v35
	global_atomic_add_f32 v[38:39], v32, off
	global_atomic_add_f32 v[36:37], v33, off
; __device__ __forceinline__ unsigned cvt_pk_bf16(float lo, float hi) { unsigned r; asm volatile("v_cvt_pk_bf16_f32 %0, %1, %2" : "=v"(r) : "v"(lo), "v"(hi)); return r; }
;     __device__ __forceinline__ void operator()(const f32x4 (&acc)[2][2][4][2], const Unit& u, int wr, int wc, int fr, int fq) const {
;     ...
;             for (int m = 0; m < 4; ++m) { const int ra = rowA + ai * HALF + m * 16, rb = rowB + ai * HALF + m * 16; const size_t offA = (size_t)ra * 1024 + col0, offB = (size_t)rb * 1024 + col0;
;                 float ssa = 0.f, ssb = 0.f;
; #pragma unroll
;                 for (int bj = 0; bj < 2; ++bj) {
;                     const f32x4 x0 = acc[ai][bj][m][0], x1 = acc[ai][bj][m][1]; f32x4 za, zb;
; #pragma unroll
;                     for (int e = 0; e < 4; ++e) { const float s1 = __shfl_xor(x1[e], 8), s0 = __shfl_xor(x0[e], 8); za[e] = hi8 ? s1 : x0[e]; zb[e] = hi8 ? x1[e] : s0; }
;                     const f32x4 ba = *(const f32x4*)(base + offA + bj * HALF), bb = *(const f32x4*)(base + offB + bj * HALF);
;                     const f32x4 oa = ba + gs[bj] * za, ob = bb + gs[bj] * zb;
;                     *(f32x4*)(out + offA + bj * HALF) = oa; *(f32x4*)(out + offB + bj * HALF) = ob;
;                     const f32x4 ha = oa * av[bj], hb = ob * av[bj];
;                     *(unsigned long long*)(Hn + offA + bj * HALF) = (unsigned long long)cvt_pk_bf16(ha[0], ha[1]) | ((unsigned long long)cvt_pk_bf16(ha[2], ha[3]) << 32);
;                     *(unsigned long long*)(Hn + offB + bj * HALF) = (unsigned long long)cvt_pk_bf16(hb[0], hb[1]) | ((unsigned long long)cvt_pk_bf16(hb[2], hb[3]) << 32);
;                     ssa += (oa[0] * oa[0] + oa[1] * oa[1]) + (oa[2] * oa[2] + oa[3] * oa[3]); ssb += (ob[0] * ob[0] + ob[1] * ob[1]) + (ob[2] * ob[2] + ob[3] * ob[3]); }
;                 ssa += __shfl_xor(ssa, 8); ssa += __shfl_xor(ssa, 16); ssa += __shfl_xor(ssa, 32);
;                 ssb += __shfl_xor(ssb, 8); ssb += __shfl_xor(ssb, 16); ssb += __shfl_xor(ssb, 32);
;                 if (fq == 0 && hi8 == 0) { atomicAdd(rowss + ra, ssa); atomicAdd(rowss + rb, ssb); } }
.LBB0_555:
	s_or_b64 exec, exec, s[28:29]
	v_add_u32_e32 v32, 0xa0, v150
	s_waitcnt lgkmcnt(1)
	v_add_u32_e32 v34, 0xa8, v150
	v_ashrrev_i32_e32 v33, 31, v32
	v_lshlrev_b64 v[36:37], 10, v[32:33]
	s_waitcnt lgkmcnt(0)
	v_ashrrev_i32_e32 v35, 31, v34
	v_readlane_b32 s52, v252, 18
	v_lshl_add_u64 v[44:45], v[36:37], 0, v[148:149]
	v_lshlrev_b64 v[36:37], 10, v[34:35]
	v_readlane_b32 s53, v252, 19
	v_lshl_add_u64 v[46:47], v[36:37], 0, v[148:149]
	v_lshlrev_b64 v[56:57], 2, v[44:45]
	s_mov_b64 s[36:37], s[52:53]
	v_lshl_add_u64 v[58:59], s[36:37], 0, v[56:57]
	v_lshlrev_b64 v[60:61], 2, v[46:47]
	global_load_dwordx4 v[36:39], v[58:59], off nt
	v_lshl_add_u64 v[62:63], s[36:37], 0, v[60:61]
	global_load_dwordx4 v[40:43], v[62:63], off nt
	ds_bpermute_b32 v64, v162, v24
	ds_bpermute_b32 v65, v162, v28
	ds_bpermute_b32 v66, v162, v25
	ds_bpermute_b32 v67, v162, v29
	ds_bpermute_b32 v68, v162, v26
	ds_bpermute_b32 v70, v162, v27
	ds_bpermute_b32 v69, v162, v30
	ds_bpermute_b32 v71, v162, v31
	v_readlane_b32 s54, v252, 20
	v_readlane_b32 s55, v252, 21
	v_readlane_b32 s56, v252, 22
	v_readlane_b32 s57, v252, 23
	v_readlane_b32 s58, v252, 24
	v_readlane_b32 s59, v252, 25
	v_readlane_b32 s60, v252, 26
	v_readlane_b32 s61, v252, 27
	v_readlane_b32 s62, v252, 28
	v_readlane_b32 s63, v252, 29
	v_readlane_b32 s64, v252, 30
	v_readlane_b32 s65, v252, 31
	v_readlane_b32 s66, v252, 32
	v_readlane_b32 s67, v252, 33
	v_readlane_b32 s52, v252, 2
	s_waitcnt lgkmcnt(7)
	v_cndmask_b32_e64 v28, v64, v28, s[0:1]
	s_waitcnt lgkmcnt(6)
	v_cndmask_b32_e64 v64, v24, v65, s[0:1]
	s_waitcnt lgkmcnt(5)
	v_cndmask_b32_e64 v29, v66, v29, s[0:1]
	s_waitcnt lgkmcnt(4)
	v_cndmask_b32_e64 v65, v25, v67, s[0:1]
	s_waitcnt lgkmcnt(3)
	v_cndmask_b32_e64 v24, v68, v30, s[0:1]
	s_waitcnt lgkmcnt(2)
	v_cndmask_b32_e64 v25, v70, v31, s[0:1]
	v_readlane_b32 s62, v252, 12
	v_readlane_b32 s63, v252, 13
	v_readlane_b32 s66, v252, 16
	v_readlane_b32 s67, v252, 17
	s_waitcnt lgkmcnt(1)
	v_cndmask_b32_e64 v30, v26, v69, s[0:1]
	s_waitcnt lgkmcnt(0)
	v_cndmask_b32_e64 v31, v27, v71, s[0:1]
	s_mov_b64 s[62:63], s[66:67]
	v_lshl_add_u64 v[44:45], v[44:45], 1, s[4:5]
	v_lshl_add_u64 v[46:47], v[46:47], 1, s[4:5]
	v_lshl_add_u64 v[56:57], s[62:63], 0, v[56:57]
	v_lshl_add_u64 v[60:61], s[62:63], 0, v[60:61]
	ds_bpermute_b32 v66, v162, v19
	ds_bpermute_b32 v67, v162, v23
	v_readlane_b32 s53, v252, 3
	v_readlane_b32 s54, v252, 4
	v_readlane_b32 s55, v252, 5
	v_readlane_b32 s56, v252, 6
	v_readlane_b32 s57, v252, 7
	v_readlane_b32 s58, v252, 8
	v_readlane_b32 s59, v252, 9
	v_readlane_b32 s60, v252, 10
	v_readlane_b32 s61, v252, 11
	v_readlane_b32 s64, v252, 14
	v_readlane_b32 s65, v252, 15
	s_waitcnt vmcnt(1)
	v_pk_fma_f32 v[26:27], v[50:51], v[24:25], v[38:39]
	v_pk_fma_f32 v[24:25], v[48:49], v[28:29], v[36:37]
	s_waitcnt vmcnt(0)
	v_pk_fma_f32 v[30:31], v[50:51], v[30:31], v[42:43]
	v_pk_fma_f32 v[28:29], v[48:49], v[64:65], v[40:41]
	v_pk_mul_f32 v[36:37], v[128:129], v[26:27]
	v_pk_mul_f32 v[38:39], v[130:131], v[24:25]
	global_store_dwordx4 v[56:57], v[24:27], off sc1
	global_store_dwordx4 v[60:61], v[28:31], off sc1
	v_pk_mul_f32 v[40:41], v[128:129], v[30:31]
	v_pk_mul_f32 v[42:43], v[130:131], v[28:29]
	v_cvt_pk_bf16_f32 v38, v38, v39
	v_cvt_pk_bf16_f32 v39, v36, v37
	global_store_dwordx2 v[44:45], v[38:39], off
	v_cvt_pk_bf16_f32 v36, v42, v43
	v_cvt_pk_bf16_f32 v37, v40, v41
	global_store_dwordx2 v[46:47], v[36:37], off
	global_load_dwordx4 v[36:39], v[58:59], off offset:512 nt
	s_nop 0
	global_load_dwordx4 v[40:43], v[62:63], off offset:512 nt
	ds_bpermute_b32 v58, v162, v16
	ds_bpermute_b32 v59, v162, v20
	ds_bpermute_b32 v63, v162, v21
	ds_bpermute_b32 v64, v162, v18
	ds_bpermute_b32 v65, v162, v22
	ds_bpermute_b32 v62, v162, v17
	s_waitcnt lgkmcnt(5)
	v_cndmask_b32_e64 v20, v58, v20, s[0:1]
	s_waitcnt lgkmcnt(4)
	v_cndmask_b32_e64 v58, v16, v59, s[0:1]
	s_waitcnt lgkmcnt(3)
	v_cndmask_b32_e64 v59, v17, v63, s[0:1]
	s_waitcnt lgkmcnt(2)
	v_cndmask_b32_e64 v16, v64, v22, s[0:1]
	s_waitcnt lgkmcnt(1)
	v_cndmask_b32_e64 v22, v18, v65, s[0:1]
	v_cndmask_b32_e64 v17, v66, v23, s[0:1]
	v_cndmask_b32_e64 v23, v19, v67, s[0:1]
	v_mul_f32_e32 v18, v25, v25
	v_mul_f32_e32 v19, v27, v27
	s_waitcnt lgkmcnt(0)
	v_cndmask_b32_e64 v21, v62, v21, s[0:1]
	v_mul_f32_e32 v25, v29, v29
	v_mul_f32_e32 v27, v31, v31
	v_fmac_f32_e32 v18, v24, v24
	v_fmac_f32_e32 v19, v26, v26
	v_fmac_f32_e32 v25, v28, v28
	v_fmac_f32_e32 v27, v30, v30
	v_add_f32_e32 v24, v18, v19
	v_add_f32_e32 v25, v25, v27
	s_waitcnt vmcnt(1)
	v_pk_fma_f32 v[18:19], v[54:55], v[16:17], v[38:39]
	v_pk_fma_f32 v[16:17], v[52:53], v[20:21], v[36:37]
	s_waitcnt vmcnt(0)
	v_pk_fma_f32 v[22:23], v[54:55], v[22:23], v[42:43]
	v_pk_fma_f32 v[20:21], v[52:53], v[58:59], v[40:41]
	v_mul_f32_e32 v26, v17, v17
	v_mul_f32_e32 v27, v19, v19
	v_mul_f32_e32 v28, v21, v21
	v_mul_f32_e32 v29, v23, v23
	v_fmac_f32_e32 v26, v16, v16
	v_fmac_f32_e32 v27, v18, v18
	v_fmac_f32_e32 v28, v20, v20
	v_fmac_f32_e32 v29, v22, v22
	v_add_f32_e32 v26, v26, v27
	v_add_f32_e32 v27, v28, v29
	v_add_f32_e32 v24, v24, v26
	v_add_f32_e32 v25, v25, v27
	ds_bpermute_b32 v26, v162, v24
	ds_bpermute_b32 v27, v162, v25
	global_store_dwordx4 v[56:57], v[16:19], off offset:512 sc1
	global_store_dwordx4 v[60:61], v[20:23], off offset:512 sc1
	s_waitcnt lgkmcnt(1)
	v_add_f32_e32 v26, v24, v26
	s_waitcnt lgkmcnt(0)
	v_add_f32_e32 v27, v25, v27
	ds_bpermute_b32 v28, v133, v26
	ds_bpermute_b32 v29, v133, v27
	v_pk_mul_f32 v[16:17], v[120:121], v[16:17]
	v_pk_mul_f32 v[18:19], v[122:123], v[18:19]
	v_cvt_pk_bf16_f32 v24, v16, v17
	s_waitcnt lgkmcnt(1)
	v_add_f32_e32 v16, v26, v28
	s_waitcnt lgkmcnt(0)
	v_add_f32_e32 v17, v27, v29
	v_cvt_pk_bf16_f32 v25, v18, v19
	ds_bpermute_b32 v18, v132, v16
	ds_bpermute_b32 v19, v132, v17
	v_pk_mul_f32 v[20:21], v[120:121], v[20:21]
	v_pk_mul_f32 v[22:23], v[122:123], v[22:23]
	global_store_dwordx2 v[44:45], v[24:25], off offset:256
	v_cvt_pk_bf16_f32 v20, v20, v21
	v_cvt_pk_bf16_f32 v21, v22, v23
	global_store_dwordx2 v[46:47], v[20:21], off offset:256
	s_and_saveexec_b64 s[28:29], s[18:19]
	s_cbranch_execz .LBB0_557
	v_lshl_add_u64 v[22:23], v[32:33], 2, s[68:69]
	s_waitcnt lgkmcnt(1)
	v_add_f32_e32 v16, v16, v18
	v_lshl_add_u64 v[20:21], v[34:35], 2, s[68:69]
	s_waitcnt lgkmcnt(0)
	v_add_f32_e32 v17, v17, v19
	global_atomic_add_f32 v[22:23], v16, off
	global_atomic_add_f32 v[20:21], v17, off
; __device__ __forceinline__ unsigned cvt_pk_bf16(float lo, float hi) { unsigned r; asm volatile("v_cvt_pk_bf16_f32 %0, %1, %2" : "=v"(r) : "v"(lo), "v"(hi)); return r; }
;     __device__ __forceinline__ void operator()(const f32x4 (&acc)[2][2][4][2], const Unit& u, int wr, int wc, int fr, int fq) const {
;     ...
;             for (int m = 0; m < 4; ++m) { const int ra = rowA + ai * HALF + m * 16, rb = rowB + ai * HALF + m * 16; const size_t offA = (size_t)ra * 1024 + col0, offB = (size_t)rb * 1024 + col0;
;                 float ssa = 0.f, ssb = 0.f;
; #pragma unroll
;                 for (int bj = 0; bj < 2; ++bj) {
;                     const f32x4 x0 = acc[ai][bj][m][0], x1 = acc[ai][bj][m][1]; f32x4 za, zb;
; #pragma unroll
;                     for (int e = 0; e < 4; ++e) { const float s1 = __shfl_xor(x1[e], 8), s0 = __shfl_xor(x0[e], 8); za[e] = hi8 ? s1 : x0[e]; zb[e] = hi8 ? x1[e] : s0; }
;                     const f32x4 ba = *(const f32x4*)(base + offA + bj * HALF), bb = *(const f32x4*)(base + offB + bj * HALF);
;                     const f32x4 oa = ba + gs[bj] * za, ob = bb + gs[bj] * zb;
;                     *(f32x4*)(out + offA + bj * HALF) = oa; *(f32x4*)(out + offB + bj * HALF) = ob;
;                     const f32x4 ha = oa * av[bj], hb = ob * av[bj];
;                     *(unsigned long long*)(Hn + offA + bj * HALF) = (unsigned long long)cvt_pk_bf16(ha[0], ha[1]) | ((unsigned long long)cvt_pk_bf16(ha[2], ha[3]) << 32);
;                     *(unsigned long long*)(Hn + offB + bj * HALF) = (unsigned long long)cvt_pk_bf16(hb[0], hb[1]) | ((unsigned long long)cvt_pk_bf16(hb[2], hb[3]) << 32);
;                     ssa += (oa[0] * oa[0] + oa[1] * oa[1]) + (oa[2] * oa[2] + oa[3] * oa[3]); ssb += (ob[0] * ob[0] + ob[1] * ob[1]) + (ob[2] * ob[2] + ob[3] * ob[3]); }
;                 ssa += __shfl_xor(ssa, 8); ssa += __shfl_xor(ssa, 16); ssa += __shfl_xor(ssa, 32);
;                 ssb += __shfl_xor(ssb, 8); ssb += __shfl_xor(ssb, 16); ssb += __shfl_xor(ssb, 32);
;                 if (fq == 0 && hi8 == 0) { atomicAdd(rowss + ra, ssa); atomicAdd(rowss + rb, ssb); } }
.LBB0_557:
	s_or_b64 exec, exec, s[28:29]
	v_add_u32_e32 v16, 0xb0, v150
	s_waitcnt lgkmcnt(1)
	v_add_u32_e32 v18, 0xb8, v150
	v_ashrrev_i32_e32 v17, 31, v16
	v_lshlrev_b64 v[20:21], 10, v[16:17]
	s_waitcnt lgkmcnt(0)
	v_ashrrev_i32_e32 v19, 31, v18
	v_readlane_b32 s52, v252, 18
	v_lshl_add_u64 v[28:29], v[20:21], 0, v[148:149]
	v_lshlrev_b64 v[20:21], 10, v[18:19]
	v_readlane_b32 s53, v252, 19
	v_lshl_add_u64 v[30:31], v[20:21], 0, v[148:149]
	v_lshlrev_b64 v[32:33], 2, v[28:29]
	s_mov_b64 s[36:37], s[52:53]
	v_lshl_add_u64 v[34:35], s[36:37], 0, v[32:33]
	v_lshlrev_b64 v[36:37], 2, v[30:31]
	global_load_dwordx4 v[20:23], v[34:35], off nt
	v_lshl_add_u64 v[38:39], s[36:37], 0, v[36:37]
	global_load_dwordx4 v[24:27], v[38:39], off nt
	ds_bpermute_b32 v40, v162, v8
	ds_bpermute_b32 v41, v162, v12
	ds_bpermute_b32 v42, v162, v9
	ds_bpermute_b32 v43, v162, v13
	ds_bpermute_b32 v44, v162, v10
	ds_bpermute_b32 v46, v162, v11
	ds_bpermute_b32 v45, v162, v14
	ds_bpermute_b32 v47, v162, v15
	v_readlane_b32 s54, v252, 20
	v_readlane_b32 s55, v252, 21
	v_readlane_b32 s56, v252, 22
	v_readlane_b32 s57, v252, 23
	v_readlane_b32 s58, v252, 24
	v_readlane_b32 s59, v252, 25
	v_readlane_b32 s60, v252, 26
	v_readlane_b32 s61, v252, 27
	v_readlane_b32 s62, v252, 28
	v_readlane_b32 s63, v252, 29
	v_readlane_b32 s64, v252, 30
	v_readlane_b32 s65, v252, 31
	v_readlane_b32 s66, v252, 32
	v_readlane_b32 s67, v252, 33
	v_readlane_b32 s52, v252, 2
	s_waitcnt lgkmcnt(7)
	v_cndmask_b32_e64 v12, v40, v12, s[0:1]
	s_waitcnt lgkmcnt(6)
	v_cndmask_b32_e64 v40, v8, v41, s[0:1]
	s_waitcnt lgkmcnt(5)
	v_cndmask_b32_e64 v13, v42, v13, s[0:1]
	s_waitcnt lgkmcnt(4)
	v_cndmask_b32_e64 v41, v9, v43, s[0:1]
	s_waitcnt lgkmcnt(3)
	v_cndmask_b32_e64 v8, v44, v14, s[0:1]
	s_waitcnt lgkmcnt(2)
	v_cndmask_b32_e64 v9, v46, v15, s[0:1]
	v_readlane_b32 s62, v252, 12
	v_readlane_b32 s63, v252, 13
	v_readlane_b32 s66, v252, 16
	v_readlane_b32 s67, v252, 17
	s_waitcnt lgkmcnt(1)
	v_cndmask_b32_e64 v14, v10, v45, s[0:1]
	s_waitcnt lgkmcnt(0)
	v_cndmask_b32_e64 v15, v11, v47, s[0:1]
	s_mov_b64 s[62:63], s[66:67]
	v_lshl_add_u64 v[28:29], v[28:29], 1, s[4:5]
	v_lshl_add_u64 v[30:31], v[30:31], 1, s[4:5]
	v_lshl_add_u64 v[32:33], s[62:63], 0, v[32:33]
	v_lshl_add_u64 v[36:37], s[62:63], 0, v[36:37]
	ds_bpermute_b32 v42, v162, v3
	ds_bpermute_b32 v43, v162, v7
	v_readlane_b32 s53, v252, 3
	v_readlane_b32 s54, v252, 4
	v_readlane_b32 s55, v252, 5
	v_readlane_b32 s56, v252, 6
	v_readlane_b32 s57, v252, 7
	v_readlane_b32 s58, v252, 8
	v_readlane_b32 s59, v252, 9
	v_readlane_b32 s60, v252, 10
	v_readlane_b32 s61, v252, 11
	v_readlane_b32 s64, v252, 14
	v_readlane_b32 s65, v252, 15
	s_waitcnt vmcnt(1)
	v_pk_fma_f32 v[10:11], v[50:51], v[8:9], v[22:23]
	v_pk_fma_f32 v[8:9], v[48:49], v[12:13], v[20:21]
	s_waitcnt vmcnt(0)
	v_pk_fma_f32 v[14:15], v[50:51], v[14:15], v[26:27]
	v_pk_fma_f32 v[12:13], v[48:49], v[40:41], v[24:25]
	v_pk_mul_f32 v[20:21], v[128:129], v[10:11]
	v_pk_mul_f32 v[22:23], v[130:131], v[8:9]
	global_store_dwordx4 v[32:33], v[8:11], off sc1
	global_store_dwordx4 v[36:37], v[12:15], off sc1
	v_pk_mul_f32 v[24:25], v[128:129], v[14:15]
	v_pk_mul_f32 v[26:27], v[130:131], v[12:13]
	v_cvt_pk_bf16_f32 v22, v22, v23
	v_cvt_pk_bf16_f32 v23, v20, v21
	global_store_dwordx2 v[28:29], v[22:23], off
	v_cvt_pk_bf16_f32 v20, v26, v27
	v_cvt_pk_bf16_f32 v21, v24, v25
	global_store_dwordx2 v[30:31], v[20:21], off
	global_load_dwordx4 v[20:23], v[34:35], off offset:512 nt
	s_nop 0
	global_load_dwordx4 v[24:27], v[38:39], off offset:512 nt
	ds_bpermute_b32 v34, v162, v0
	ds_bpermute_b32 v35, v162, v4
	ds_bpermute_b32 v39, v162, v5
	ds_bpermute_b32 v40, v162, v2
	ds_bpermute_b32 v41, v162, v6
	ds_bpermute_b32 v38, v162, v1
	s_waitcnt lgkmcnt(5)
	v_cndmask_b32_e64 v4, v34, v4, s[0:1]
	s_waitcnt lgkmcnt(4)
	v_cndmask_b32_e64 v34, v0, v35, s[0:1]
	s_waitcnt lgkmcnt(3)
	v_cndmask_b32_e64 v35, v1, v39, s[0:1]
	s_waitcnt lgkmcnt(2)
	v_cndmask_b32_e64 v0, v40, v6, s[0:1]
	s_waitcnt lgkmcnt(1)
	v_cndmask_b32_e64 v6, v2, v41, s[0:1]
	v_cndmask_b32_e64 v1, v42, v7, s[0:1]
	v_cndmask_b32_e64 v7, v3, v43, s[0:1]
	v_mul_f32_e32 v2, v9, v9
	v_mul_f32_e32 v3, v11, v11
	s_waitcnt lgkmcnt(0)
	v_cndmask_b32_e64 v5, v38, v5, s[0:1]
	v_mul_f32_e32 v9, v13, v13
	v_mul_f32_e32 v11, v15, v15
	v_fmac_f32_e32 v2, v8, v8
	v_fmac_f32_e32 v3, v10, v10
	v_fmac_f32_e32 v9, v12, v12
	v_fmac_f32_e32 v11, v14, v14
	v_add_f32_e32 v8, v2, v3
	v_add_f32_e32 v9, v9, v11
	s_waitcnt vmcnt(1)
	v_pk_fma_f32 v[2:3], v[54:55], v[0:1], v[22:23]
	v_pk_fma_f32 v[0:1], v[52:53], v[4:5], v[20:21]
	s_waitcnt vmcnt(0)
	v_pk_fma_f32 v[6:7], v[54:55], v[6:7], v[26:27]
	v_pk_fma_f32 v[4:5], v[52:53], v[34:35], v[24:25]
	v_mul_f32_e32 v10, v1, v1
	v_mul_f32_e32 v11, v3, v3
	v_mul_f32_e32 v12, v5, v5
	v_mul_f32_e32 v13, v7, v7
	v_fmac_f32_e32 v10, v0, v0
	v_fmac_f32_e32 v11, v2, v2
	v_fmac_f32_e32 v12, v4, v4
	v_fmac_f32_e32 v13, v6, v6
	v_add_f32_e32 v10, v10, v11
	v_add_f32_e32 v11, v12, v13
	v_add_f32_e32 v8, v8, v10
	v_add_f32_e32 v9, v9, v11
	ds_bpermute_b32 v10, v162, v8
	ds_bpermute_b32 v11, v162, v9
	global_store_dwordx4 v[32:33], v[0:3], off offset:512 sc1
	global_store_dwordx4 v[36:37], v[4:7], off offset:512 sc1
	s_waitcnt lgkmcnt(1)
	v_add_f32_e32 v10, v8, v10
	s_waitcnt lgkmcnt(0)
	v_add_f32_e32 v11, v9, v11
	ds_bpermute_b32 v12, v133, v10
	ds_bpermute_b32 v13, v133, v11
	v_pk_mul_f32 v[0:1], v[120:121], v[0:1]
	v_pk_mul_f32 v[2:3], v[122:123], v[2:3]
	v_cvt_pk_bf16_f32 v8, v0, v1
	s_waitcnt lgkmcnt(1)
	v_add_f32_e32 v0, v10, v12
	s_waitcnt lgkmcnt(0)
	v_add_f32_e32 v1, v11, v13
	v_cvt_pk_bf16_f32 v9, v2, v3
	ds_bpermute_b32 v2, v132, v0
	ds_bpermute_b32 v3, v132, v1
	v_pk_mul_f32 v[4:5], v[120:121], v[4:5]
	v_pk_mul_f32 v[6:7], v[122:123], v[6:7]
	global_store_dwordx2 v[28:29], v[8:9], off offset:256
	v_cvt_pk_bf16_f32 v4, v4, v5
	v_cvt_pk_bf16_f32 v5, v6, v7
	global_store_dwordx2 v[30:31], v[4:5], off offset:256
	s_and_saveexec_b64 s[28:29], s[18:19]
	s_cbranch_execz .LBB0_559
	v_lshl_add_u64 v[6:7], v[16:17], 2, s[68:69]
	s_waitcnt lgkmcnt(1)
	v_add_f32_e32 v0, v0, v2
	v_lshl_add_u64 v[4:5], v[18:19], 2, s[68:69]
	s_waitcnt lgkmcnt(0)
	v_add_f32_e32 v1, v1, v3
	global_atomic_add_f32 v[6:7], v0, off
	global_atomic_add_f32 v[4:5], v1, off

;     __device__ __forceinline__ void operator()(const f32x4 (&acc)[2][2][4][2], const Unit& u, int wr, int wc, int fr, int fq) const {
;         const int hi8 = fr >> 3;
;         const int rowA = u.pm * BM + wr * 64 + (fr & 7), rowB = rowA + 8; const int col0 = u.pn * BM + wc * 32 + 16 * hi8 + 4 * fq;
;         const float* gb = gate + (size_t)((u.pm * BM) / 8192) * 3072 + col0;
;         f32x4 gs[2];
; #pragma unroll
;         for (int bj = 0; bj < 2; ++bj) gs[bj] = *(const f32x4*)(gb + bj * HALF);
; #pragma unroll
;         for (int ai = 0; ai < 2; ++ai)
; #pragma unroll
;             for (int m = 0; m < 4; ++m) { const size_t offA = (size_t)(rowA + ai * HALF + m * 16) * 1024 + col0, offB = (size_t)(rowB + ai * HALF + m * 16) * 1024 + col0;
; #pragma unroll
;                 for (int bj = 0; bj < 2; ++bj) {
;                     const f32x4 x0 = acc[ai][bj][m][0], x1 = acc[ai][bj][m][1]; f32x4 za, zb;
; #pragma unroll
;                     for (int e = 0; e < 4; ++e) {
;                         const float s1 = __shfl_xor(x1[e], 8), s0 = __shfl_xor(x0[e], 8);
;                         za[e] = hi8 ? s1 : x0[e];
;                         zb[e] = hi8 ? x1[e] : s0; }
;                     const f32x4 ba = *(const f32x4*)(base + offA + bj * HALF), bb = *(const f32x4*)(base + offB + bj * HALF);
;                     *(f32x4*)(out + offA + bj * HALF) = ba + gs[bj] * za;
;                     *(f32x4*)(out + offB + bj * HALF) = bb + gs[bj] * zb; } }
.LBB0_819:
	s_ashr_i32 s27, s36, 31
	s_lshr_b32 s27, s27, 27
	s_add_i32 s27, s36, s27
	v_lshl_add_u32 v152, s36, 8, v159
	s_ashr_i32 s27, s27, 5
	v_readlane_b32 s76, v252, 2
	v_lshl_add_u32 v104, s64, 8, v160
	s_mul_hi_i32 s29, s27, 0x3000
	s_mulk_i32 s27, 0x3000
	v_ashrrev_i32_e32 v153, 31, v152
	v_readlane_b32 s90, v252, 16
	v_readlane_b32 s91, v252, 17
	s_add_u32 s38, s49, s27
	v_ashrrev_i32_e32 v105, 31, v104
	v_or_b32_e32 v110, 8, v152
	v_lshlrev_b64 v[148:149], 12, v[152:153]
	s_mov_b64 s[66:67], s[90:91]
	s_addc_u32 s39, s50, s29
	v_lshlrev_b64 v[150:151], 2, v[104:105]
	v_ashrrev_i32_e32 v111, 31, v110
	v_lshl_add_u64 v[148:149], s[66:67], 0, v[148:149]
	v_lshl_add_u64 v[108:109], s[38:39], 0, v[150:151]
	v_lshl_add_u64 v[148:149], v[148:149], 0, v[150:151]
	v_lshlrev_b64 v[110:111], 12, v[110:111]
	global_load_dwordx4 v[104:107], v[108:109], off nt
	global_load_dwordx4 v[166:169], v[148:149], off nt
	v_lshl_add_u64 v[110:111], s[66:67], 0, v[110:111]
	v_lshl_add_u64 v[156:157], v[110:111], 0, v[150:151]
	global_load_dwordx4 v[170:173], v[156:157], off nt
	s_nop 0
	global_load_dwordx4 v[108:111], v[108:109], off offset:512 nt
	s_nop 0
	global_load_dwordx4 v[174:177], v[148:149], off offset:512 nt
	global_load_dwordx4 v[178:181], v[156:157], off offset:512 nt
	v_and_b32_e32 v154, 64, v164
	v_xor_b32_e32 v153, 8, v164
	v_add_u32_e32 v155, 64, v154
	v_or_b32_e32 v154, 16, v152
	v_cmp_lt_i32_e32 vcc, v153, v155
	v_ashrrev_i32_e32 v155, 31, v154
	v_lshlrev_b64 v[154:155], 12, v[154:155]
	v_or_b32_e32 v186, 24, v152
	v_lshl_add_u64 v[154:155], s[66:67], 0, v[154:155]
	v_ashrrev_i32_e32 v187, 31, v186
	v_lshl_add_u64 v[198:199], v[154:155], 0, v[150:151]
	global_load_dwordx4 v[182:185], v[198:199], off nt
	v_lshlrev_b64 v[154:155], 12, v[186:187]
	v_lshl_add_u64 v[154:155], s[66:67], 0, v[154:155]
	v_lshl_add_u64 v[154:155], v[154:155], 0, v[150:151]
	global_load_dwordx4 v[186:189], v[154:155], off nt
	global_load_dwordx4 v[190:193], v[198:199], off offset:512 nt
	global_load_dwordx4 v[194:197], v[154:155], off offset:512 nt
	v_cndmask_b32_e32 v153, v164, v153, vcc
	v_lshlrev_b32_e32 v153, 2, v153
	ds_bpermute_b32 v165, v153, v128
	ds_bpermute_b32 v201, v153, v129
	ds_bpermute_b32 v203, v153, v130
	ds_bpermute_b32 v205, v153, v131
	ds_bpermute_b32 v200, v153, v132
	ds_bpermute_b32 v202, v153, v133
	ds_bpermute_b32 v204, v153, v134
	ds_bpermute_b32 v206, v153, v135
	ds_bpermute_b32 v207, v153, v120
	ds_bpermute_b32 v208, v153, v124
	ds_bpermute_b32 v209, v153, v121
	ds_bpermute_b32 v210, v153, v125
	ds_bpermute_b32 v211, v153, v122
	ds_bpermute_b32 v212, v153, v126
	ds_bpermute_b32 v213, v153, v123
	ds_bpermute_b32 v214, v153, v127
	s_waitcnt lgkmcnt(0)
	v_cndmask_b32_e64 v132, v165, v132, s[0:1]
	v_cndmask_b32_e64 v133, v201, v133, s[0:1]
	v_cndmask_b32_e64 v134, v203, v134, s[0:1]
	v_cndmask_b32_e64 v135, v205, v135, s[0:1]
	v_cndmask_b32_e64 v128, v128, v200, s[0:1]
	v_cndmask_b32_e64 v129, v129, v202, s[0:1]
	v_cndmask_b32_e64 v130, v130, v204, s[0:1]
	v_cndmask_b32_e64 v131, v131, v206, s[0:1]
	v_cndmask_b32_e64 v200, v207, v124, s[0:1]
	v_cndmask_b32_e64 v202, v120, v208, s[0:1]
	v_cndmask_b32_e64 v201, v209, v125, s[0:1]
	v_cndmask_b32_e64 v203, v121, v210, s[0:1]
	v_cndmask_b32_e64 v204, v211, v126, s[0:1]
	v_cndmask_b32_e64 v206, v122, v212, s[0:1]
	v_cndmask_b32_e64 v205, v213, v127, s[0:1]
	v_cndmask_b32_e64 v207, v123, v214, s[0:1]
	ds_bpermute_b32 v165, v153, v112
	v_readlane_b32 s77, v252, 3
	v_readlane_b32 s78, v252, 4
	v_readlane_b32 s79, v252, 5
	v_readlane_b32 s80, v252, 6
	v_readlane_b32 s81, v252, 7
	v_readlane_b32 s82, v252, 8
	v_readlane_b32 s83, v252, 9
	v_readlane_b32 s84, v252, 10
	v_readlane_b32 s85, v252, 11
	v_readlane_b32 s86, v252, 12
	v_readlane_b32 s87, v252, 13
	v_readlane_b32 s88, v252, 14
	v_readlane_b32 s89, v252, 15
	s_waitcnt vmcnt(0)
	v_pk_fma_f32 v[122:123], v[106:107], v[134:135], v[168:169]
	v_pk_fma_f32 v[120:121], v[104:105], v[132:133], v[166:167]
	v_pk_fma_f32 v[126:127], v[106:107], v[130:131], v[172:173]
	v_pk_fma_f32 v[124:125], v[104:105], v[128:129], v[170:171]
	v_pk_fma_f32 v[130:131], v[110:111], v[204:205], v[176:177]
	v_pk_fma_f32 v[128:129], v[108:109], v[200:201], v[174:175]
	global_store_dwordx4 v[148:149], v[120:123], off sc1
	global_store_dwordx4 v[156:157], v[124:127], off sc1
	global_store_dwordx4 v[148:149], v[128:131], off offset:512 sc1
	v_or_b32_e32 v120, 32, v152
	v_ashrrev_i32_e32 v121, 31, v120
	v_lshlrev_b64 v[120:121], 12, v[120:121]
	v_or_b32_e32 v126, 40, v152
	v_lshl_add_u64 v[120:121], s[66:67], 0, v[120:121]
	v_ashrrev_i32_e32 v127, 31, v126
	v_lshl_add_u64 v[134:135], v[120:121], 0, v[150:151]
	global_load_dwordx4 v[122:125], v[134:135], off nt
	v_lshlrev_b64 v[120:121], 12, v[126:127]
	v_lshl_add_u64 v[120:121], s[66:67], 0, v[120:121]
	v_lshl_add_u64 v[120:121], v[120:121], 0, v[150:151]
	ds_bpermute_b32 v166, v153, v116
	global_load_dwordx4 v[126:129], v[120:121], off nt
	v_pk_fma_f32 v[132:133], v[110:111], v[206:207], v[180:181]
	v_pk_fma_f32 v[130:131], v[108:109], v[202:203], v[178:179]
	ds_bpermute_b32 v167, v153, v113
	global_store_dwordx4 v[156:157], v[130:133], off offset:512 sc1
	s_waitcnt lgkmcnt(1)
	v_cndmask_b32_e64 v156, v112, v166, s[0:1]
	ds_bpermute_b32 v112, v153, v117
	ds_bpermute_b32 v130, v153, v114
	ds_bpermute_b32 v132, v153, v115
	ds_bpermute_b32 v131, v153, v118
	ds_bpermute_b32 v133, v153, v119
	v_cndmask_b32_e64 v116, v165, v116, s[0:1]
	s_waitcnt lgkmcnt(5)
	v_cndmask_b32_e64 v117, v167, v117, s[0:1]
	s_waitcnt lgkmcnt(4)
	v_cndmask_b32_e64 v157, v113, v112, s[0:1]
	s_waitcnt lgkmcnt(3)
	v_cndmask_b32_e64 v112, v130, v118, s[0:1]
	s_waitcnt lgkmcnt(2)
;     __device__ __forceinline__ void operator()(const f32x4 (&acc)[2][2][4][2], const Unit& u, int wr, int wc, int fr, int fq) const {
;     ...
;                 for (int bj = 0; bj < 2; ++bj) {
;                     const f32x4 x0 = acc[ai][bj][m][0], x1 = acc[ai][bj][m][1]; f32x4 za, zb;
; #pragma unroll
;                     for (int e = 0; e < 4; ++e) {
;                         const float s1 = __shfl_xor(x1[e], 8), s0 = __shfl_xor(x0[e], 8);
;                         za[e] = hi8 ? s1 : x0[e];
;                         zb[e] = hi8 ? x1[e] : s0; }
;                     const f32x4 ba = *(const f32x4*)(base + offA + bj * HALF), bb = *(const f32x4*)(base + offB + bj * HALF);
;                     *(f32x4*)(out + offA + bj * HALF) = ba + gs[bj] * za;
;                     *(f32x4*)(out + offB + bj * HALF) = bb + gs[bj] * zb; } }
	v_cndmask_b32_e64 v113, v132, v119, s[0:1]
	s_waitcnt lgkmcnt(1)
	v_cndmask_b32_e64 v130, v114, v131, s[0:1]
	s_waitcnt lgkmcnt(0)
	v_cndmask_b32_e64 v131, v115, v133, s[0:1]
	v_pk_fma_f32 v[114:115], v[106:107], v[112:113], v[184:185]
	v_pk_fma_f32 v[112:113], v[104:105], v[116:117], v[182:183]
	global_load_dwordx4 v[116:119], v[134:135], off offset:512 nt
	ds_bpermute_b32 v166, v153, v100
	global_store_dwordx4 v[198:199], v[112:115], off sc1
	ds_bpermute_b32 v165, v153, v96
	s_waitcnt lgkmcnt(0)
	v_cndmask_b32_e64 v100, v165, v100, s[0:1]
	v_pk_fma_f32 v[114:115], v[106:107], v[130:131], v[188:189]
	global_load_dwordx4 v[130:133], v[120:121], off offset:512 nt
	v_pk_fma_f32 v[112:113], v[104:105], v[156:157], v[186:187]
	ds_bpermute_b32 v157, v153, v97
	global_store_dwordx4 v[154:155], v[112:115], off sc1
	v_cndmask_b32_e64 v156, v96, v166, s[0:1]
	ds_bpermute_b32 v96, v153, v101
	ds_bpermute_b32 v112, v153, v98
	ds_bpermute_b32 v114, v153, v99
	ds_bpermute_b32 v113, v153, v102
	ds_bpermute_b32 v115, v153, v103
	s_waitcnt lgkmcnt(5)
	v_cndmask_b32_e64 v101, v157, v101, s[0:1]
	s_waitcnt lgkmcnt(4)
	v_cndmask_b32_e64 v157, v97, v96, s[0:1]
	s_waitcnt lgkmcnt(3)
	v_cndmask_b32_e64 v96, v112, v102, s[0:1]
	s_waitcnt lgkmcnt(2)
	v_cndmask_b32_e64 v97, v114, v103, s[0:1]
	s_waitcnt lgkmcnt(1)
	v_cndmask_b32_e64 v102, v98, v113, s[0:1]
	s_waitcnt lgkmcnt(0)
	v_cndmask_b32_e64 v103, v99, v115, s[0:1]
	v_pk_fma_f32 v[98:99], v[110:111], v[96:97], v[192:193]
	v_pk_fma_f32 v[96:97], v[108:109], v[100:101], v[190:191]
	global_store_dwordx4 v[198:199], v[96:99], off offset:512 sc1
	v_pk_fma_f32 v[100:101], v[110:111], v[102:103], v[196:197]
	s_nop 0
	v_or_b32_e32 v96, 48, v152
	v_ashrrev_i32_e32 v97, 31, v96
	v_or_b32_e32 v98, 56, v152
	v_lshlrev_b64 v[96:97], 12, v[96:97]
	v_lshl_add_u64 v[96:97], s[66:67], 0, v[96:97]
	v_ashrrev_i32_e32 v99, 31, v98
	v_lshl_add_u64 v[102:103], v[96:97], 0, v[150:151]
	v_lshlrev_b64 v[96:97], 12, v[98:99]
	v_lshl_add_u64 v[96:97], s[66:67], 0, v[96:97]
	global_load_dwordx4 v[112:115], v[102:103], off nt
	v_lshl_add_u64 v[96:97], v[96:97], 0, v[150:151]
	ds_bpermute_b32 v150, v153, v88
	ds_bpermute_b32 v151, v153, v92
	global_load_dwordx4 v[166:169], v[96:97], off nt
	v_pk_fma_f32 v[98:99], v[108:109], v[156:157], v[194:195]
	ds_bpermute_b32 v152, v153, v89
	global_store_dwordx4 v[154:155], v[98:101], off offset:512 sc1
	s_waitcnt lgkmcnt(2)
	v_cndmask_b32_e64 v92, v150, v92, s[0:1]
	s_waitcnt lgkmcnt(1)
	v_cndmask_b32_e64 v150, v88, v151, s[0:1]
	ds_bpermute_b32 v88, v153, v93
	ds_bpermute_b32 v98, v153, v90
	ds_bpermute_b32 v100, v153, v91
	ds_bpermute_b32 v99, v153, v94
	ds_bpermute_b32 v101, v153, v95
	s_waitcnt lgkmcnt(5)
	v_cndmask_b32_e64 v93, v152, v93, s[0:1]
	s_waitcnt lgkmcnt(4)
	v_cndmask_b32_e64 v151, v89, v88, s[0:1]
	s_waitcnt lgkmcnt(3)
	v_cndmask_b32_e64 v88, v98, v94, s[0:1]
	s_waitcnt lgkmcnt(2)
	v_cndmask_b32_e64 v89, v100, v95, s[0:1]
	s_waitcnt lgkmcnt(1)
	v_cndmask_b32_e64 v98, v90, v99, s[0:1]
	s_waitcnt lgkmcnt(0)
	v_cndmask_b32_e64 v99, v91, v101, s[0:1]
	s_waitcnt vmcnt(10)
	v_pk_fma_f32 v[90:91], v[106:107], v[88:89], v[124:125]
	v_pk_fma_f32 v[88:89], v[104:105], v[92:93], v[122:123]
	global_load_dwordx4 v[92:95], v[102:103], off offset:512 nt
	ds_bpermute_b32 v122, v153, v80
	ds_bpermute_b32 v123, v153, v84
	global_store_dwordx4 v[134:135], v[88:91], off sc1
	ds_bpermute_b32 v124, v153, v81
	ds_bpermute_b32 v125, v153, v76
	s_waitcnt vmcnt(11)
	v_pk_fma_f32 v[90:91], v[106:107], v[98:99], v[128:129]
	global_load_dwordx4 v[98:101], v[96:97], off offset:512 nt
	v_pk_fma_f32 v[88:89], v[104:105], v[150:151], v[126:127]
	global_store_dwordx4 v[120:121], v[88:91], off sc1
	s_waitcnt lgkmcnt(3)
	v_cndmask_b32_e64 v84, v122, v84, s[0:1]
	s_waitcnt lgkmcnt(2)
	v_cndmask_b32_e64 v122, v80, v123, s[0:1]
	ds_bpermute_b32 v80, v153, v85
	ds_bpermute_b32 v88, v153, v82
	ds_bpermute_b32 v90, v153, v83
	ds_bpermute_b32 v89, v153, v86
	ds_bpermute_b32 v91, v153, v87
	s_waitcnt lgkmcnt(6)
	v_cndmask_b32_e64 v85, v124, v85, s[0:1]
	s_waitcnt lgkmcnt(4)
	v_cndmask_b32_e64 v123, v81, v80, s[0:1]
	s_waitcnt lgkmcnt(3)
	v_cndmask_b32_e64 v80, v88, v86, s[0:1]
	s_waitcnt lgkmcnt(2)
	v_cndmask_b32_e64 v81, v90, v87, s[0:1]
	s_waitcnt lgkmcnt(1)
	v_cndmask_b32_e64 v86, v82, v89, s[0:1]
	s_waitcnt lgkmcnt(0)
	v_cndmask_b32_e64 v87, v83, v91, s[0:1]
	s_waitcnt vmcnt(11)
	v_pk_fma_f32 v[82:83], v[110:111], v[80:81], v[118:119]
	v_pk_fma_f32 v[80:81], v[108:109], v[84:85], v[116:117]
	v_add_co_u32_e32 v116, vcc, s56, v148
	global_store_dwordx4 v[134:135], v[80:83], off offset:512 sc1
	s_nop 0
	v_addc_co_u32_e32 v117, vcc, 0, v149, vcc
	v_add_co_u32_e32 v118, vcc, s57, v148
	s_waitcnt vmcnt(10)
	v_pk_fma_f32 v[82:83], v[110:111], v[86:87], v[132:133]
	global_load_dwordx4 v[84:87], v[116:117], off nt
	v_addc_co_u32_e32 v119, vcc, 0, v149, vcc
	global_load_dwordx4 v[88:91], v[118:119], off nt
	v_pk_fma_f32 v[80:81], v[108:109], v[122:123], v[130:131]
	ds_bpermute_b32 v124, v153, v72
	ds_bpermute_b32 v122, v153, v73
	global_store_dwordx4 v[120:121], v[80:83], off offset:512 sc1
	v_cndmask_b32_e64 v120, v72, v125, s[0:1]
	ds_bpermute_b32 v72, v153, v77
	ds_bpermute_b32 v80, v153, v74
	ds_bpermute_b32 v82, v153, v75
	ds_bpermute_b32 v81, v153, v78
	ds_bpermute_b32 v83, v153, v79
	s_waitcnt lgkmcnt(6)
	v_cndmask_b32_e64 v76, v124, v76, s[0:1]
	s_waitcnt lgkmcnt(5)
	v_cndmask_b32_e64 v77, v122, v77, s[0:1]
	s_waitcnt lgkmcnt(4)
	v_cndmask_b32_e64 v121, v73, v72, s[0:1]
	s_waitcnt lgkmcnt(3)
	v_cndmask_b32_e64 v72, v80, v78, s[0:1]
	s_waitcnt lgkmcnt(2)
	v_cndmask_b32_e64 v73, v82, v79, s[0:1]
	s_waitcnt lgkmcnt(1)
;     __device__ __forceinline__ void operator()(const f32x4 (&acc)[2][2][4][2], const Unit& u, int wr, int wc, int fr, int fq) const {
;     ...
;                 for (int bj = 0; bj < 2; ++bj) {
;                     const f32x4 x0 = acc[ai][bj][m][0], x1 = acc[ai][bj][m][1]; f32x4 za, zb;
; #pragma unroll
;                     for (int e = 0; e < 4; ++e) {
;                         const float s1 = __shfl_xor(x1[e], 8), s0 = __shfl_xor(x0[e], 8);
;                         za[e] = hi8 ? s1 : x0[e];
;                         zb[e] = hi8 ? x1[e] : s0; }
;                     const f32x4 ba = *(const f32x4*)(base + offA + bj * HALF), bb = *(const f32x4*)(base + offB + bj * HALF);
;                     *(f32x4*)(out + offA + bj * HALF) = ba + gs[bj] * za;
;                     *(f32x4*)(out + offB + bj * HALF) = bb + gs[bj] * zb; } }
	v_cndmask_b32_e64 v78, v74, v81, s[0:1]
	s_waitcnt lgkmcnt(0)
	v_cndmask_b32_e64 v79, v75, v83, s[0:1]
	ds_bpermute_b32 v123, v153, v68
	ds_bpermute_b32 v122, v153, v64
	s_waitcnt vmcnt(10)
	v_pk_fma_f32 v[74:75], v[106:107], v[72:73], v[114:115]
	v_pk_fma_f32 v[72:73], v[104:105], v[76:77], v[112:113]
	v_lshl_add_u64 v[112:113], v[148:149], 0, s[10:11]
	global_store_dwordx4 v[102:103], v[72:75], off sc1
	global_load_dwordx4 v[72:75], v[112:113], off offset:512 nt
	v_lshl_add_u64 v[114:115], v[148:149], 0, s[12:13]
	global_load_dwordx4 v[80:83], v[114:115], off offset:512 nt
	s_waitcnt vmcnt(12)
	v_pk_fma_f32 v[78:79], v[106:107], v[78:79], v[168:169]
	v_pk_fma_f32 v[76:77], v[104:105], v[120:121], v[166:167]
	ds_bpermute_b32 v121, v153, v65
	global_store_dwordx4 v[96:97], v[76:79], off sc1
	s_waitcnt lgkmcnt(2)
	v_cndmask_b32_e64 v120, v64, v123, s[0:1]
	ds_bpermute_b32 v64, v153, v69
	ds_bpermute_b32 v76, v153, v66
	ds_bpermute_b32 v78, v153, v67
	ds_bpermute_b32 v77, v153, v70
	ds_bpermute_b32 v79, v153, v71
	s_waitcnt lgkmcnt(6)
	v_cndmask_b32_e64 v68, v122, v68, s[0:1]
	s_waitcnt lgkmcnt(5)
	v_cndmask_b32_e64 v69, v121, v69, s[0:1]
	s_waitcnt lgkmcnt(4)
	v_cndmask_b32_e64 v121, v65, v64, s[0:1]
	s_waitcnt lgkmcnt(3)
	v_cndmask_b32_e64 v64, v76, v70, s[0:1]
	s_waitcnt lgkmcnt(2)
	v_cndmask_b32_e64 v65, v78, v71, s[0:1]
	s_waitcnt lgkmcnt(1)
	v_cndmask_b32_e64 v70, v66, v77, s[0:1]
	s_waitcnt lgkmcnt(0)
	v_cndmask_b32_e64 v71, v67, v79, s[0:1]
	s_waitcnt vmcnt(11)
	v_pk_fma_f32 v[66:67], v[110:111], v[64:65], v[94:95]
	v_pk_fma_f32 v[64:65], v[108:109], v[68:69], v[92:93]
	v_add_co_u32_e32 v92, vcc, s58, v148
	global_store_dwordx4 v[102:103], v[64:67], off offset:512 sc1
	s_nop 0
	v_addc_co_u32_e32 v93, vcc, 0, v149, vcc
	v_add_co_u32_e32 v94, vcc, s59, v148
	s_waitcnt vmcnt(10)
	v_pk_fma_f32 v[66:67], v[110:111], v[70:71], v[100:101]
	global_load_dwordx4 v[68:71], v[92:93], off nt
	v_addc_co_u32_e32 v95, vcc, 0, v149, vcc
	global_load_dwordx4 v[76:79], v[94:95], off nt
	ds_bpermute_b32 v101, v153, v60
	v_pk_fma_f32 v[64:65], v[108:109], v[120:121], v[98:99]
	ds_bpermute_b32 v100, v153, v56
	ds_bpermute_b32 v98, v153, v57
	global_store_dwordx4 v[96:97], v[64:67], off offset:512 sc1
	ds_bpermute_b32 v66, v153, v58
	ds_bpermute_b32 v96, v153, v59
	s_waitcnt lgkmcnt(4)
	v_cndmask_b32_e64 v64, v56, v101, s[0:1]
	ds_bpermute_b32 v56, v153, v61
	ds_bpermute_b32 v67, v153, v62
	ds_bpermute_b32 v97, v153, v63
	s_waitcnt lgkmcnt(6)
	v_cndmask_b32_e64 v60, v100, v60, s[0:1]
	s_waitcnt lgkmcnt(5)
	v_cndmask_b32_e64 v61, v98, v61, s[0:1]
	s_waitcnt lgkmcnt(2)
	v_cndmask_b32_e64 v65, v57, v56, s[0:1]
	v_cndmask_b32_e64 v56, v66, v62, s[0:1]
	v_cndmask_b32_e64 v57, v96, v63, s[0:1]
	s_waitcnt lgkmcnt(1)
	v_cndmask_b32_e64 v62, v58, v67, s[0:1]
	s_waitcnt lgkmcnt(0)
	v_cndmask_b32_e64 v63, v59, v97, s[0:1]
	s_waitcnt vmcnt(10)
	v_pk_fma_f32 v[58:59], v[106:107], v[56:57], v[86:87]
	v_pk_fma_f32 v[56:57], v[104:105], v[60:61], v[84:85]
	global_store_dwordx4 v[116:117], v[56:59], off sc1
	ds_bpermute_b32 v60, v153, v48
	ds_bpermute_b32 v61, v153, v52
	s_waitcnt vmcnt(10)
	v_pk_fma_f32 v[58:59], v[106:107], v[62:63], v[90:91]
	ds_bpermute_b32 v62, v153, v49
	v_pk_fma_f32 v[56:57], v[104:105], v[64:65], v[88:89]
	s_waitcnt lgkmcnt(2)
	v_cndmask_b32_e64 v64, v60, v52, s[0:1]
	s_waitcnt lgkmcnt(1)
	v_cndmask_b32_e64 v66, v48, v61, s[0:1]
	ds_bpermute_b32 v48, v153, v53
	s_waitcnt lgkmcnt(1)
	v_cndmask_b32_e64 v65, v62, v53, s[0:1]
	v_lshl_add_u64 v[52:53], v[148:149], 0, s[14:15]
	global_store_dwordx4 v[118:119], v[56:59], off sc1
	global_load_dwordx4 v[56:59], v[52:53], off offset:512 nt
	v_lshl_add_u64 v[84:85], v[148:149], 0, s[16:17]
	global_load_dwordx4 v[60:63], v[84:85], off offset:512 nt
	ds_bpermute_b32 v86, v153, v50
	ds_bpermute_b32 v88, v153, v51
	ds_bpermute_b32 v87, v153, v54
	ds_bpermute_b32 v89, v153, v55
	s_waitcnt lgkmcnt(4)
	v_cndmask_b32_e64 v67, v49, v48, s[0:1]
	s_waitcnt lgkmcnt(3)
	v_cndmask_b32_e64 v48, v86, v54, s[0:1]
	s_waitcnt lgkmcnt(2)
	v_cndmask_b32_e64 v49, v88, v55, s[0:1]
	s_waitcnt lgkmcnt(1)
	v_cndmask_b32_e64 v54, v50, v87, s[0:1]
	s_waitcnt lgkmcnt(0)
	v_cndmask_b32_e64 v55, v51, v89, s[0:1]
	ds_bpermute_b32 v86, v153, v41
	ds_bpermute_b32 v90, v153, v34
	s_waitcnt vmcnt(10)
	v_pk_fma_f32 v[50:51], v[110:111], v[48:49], v[74:75]
	v_pk_fma_f32 v[48:49], v[108:109], v[64:65], v[72:73]
	global_store_dwordx4 v[112:113], v[48:51], off offset:512 sc1
	ds_bpermute_b32 v91, v153, v38
	s_waitcnt vmcnt(10)
	v_pk_fma_f32 v[50:51], v[110:111], v[54:55], v[82:83]
	v_add_co_u32_e32 v54, vcc, s60, v148
	ds_bpermute_b32 v82, v153, v40
	ds_bpermute_b32 v83, v153, v44
	v_addc_co_u32_e32 v55, vcc, 0, v149, vcc
	v_pk_fma_f32 v[48:49], v[108:109], v[66:67], v[80:81]
	global_load_dwordx4 v[64:67], v[54:55], off nt
	v_add_co_u32_e32 v80, vcc, s61, v148
	global_store_dwordx4 v[114:115], v[48:51], off offset:512 sc1
	s_nop 0
	v_addc_co_u32_e32 v81, vcc, 0, v149, vcc
	global_load_dwordx4 v[72:75], v[80:81], off nt
	s_waitcnt lgkmcnt(1)
	v_cndmask_b32_e64 v44, v82, v44, s[0:1]
	s_waitcnt lgkmcnt(0)
	v_cndmask_b32_e64 v82, v40, v83, s[0:1]
	ds_bpermute_b32 v40, v153, v45
	ds_bpermute_b32 v48, v153, v42
	ds_bpermute_b32 v50, v153, v43
	ds_bpermute_b32 v49, v153, v46
	ds_bpermute_b32 v51, v153, v47
	v_cndmask_b32_e64 v45, v86, v45, s[0:1]
	s_waitcnt lgkmcnt(4)
	v_cndmask_b32_e64 v83, v41, v40, s[0:1]
	s_waitcnt lgkmcnt(3)
	v_cndmask_b32_e64 v40, v48, v46, s[0:1]
	s_waitcnt lgkmcnt(2)
	v_cndmask_b32_e64 v41, v50, v47, s[0:1]
	s_waitcnt lgkmcnt(1)
	v_cndmask_b32_e64 v46, v42, v49, s[0:1]
	s_waitcnt lgkmcnt(0)
	v_cndmask_b32_e64 v47, v43, v51, s[0:1]
	s_waitcnt vmcnt(10)
; #define PG8_BAR __builtin_amdgcn_s_barrier()
; template <class Epi, class Sched, bool ALIGN_EPI = false, bool SP2 = false>
; __device__ __forceinline__ void gemm_phase(PG8_LAS unsigned char* lds, const Gemm g, const Sched& S, const Epi& E, const int wid) {
;     ...
;         if (!has_next) break;
; #pragma unroll
;         for (int a = 0; a < 2; ++a)
; #pragma unroll
;             for (int b = 0; b < 2; ++b)
; #pragma unroll
;                 for (int m = 0; m < 4; ++m)
; #pragma unroll
;                     for (int n = 0; n < 2; ++n) acc[a][b][m][n] = (f32x4){0.f, 0.f, 0.f, 0.f};
;         cur = nxt; cA = nA; cB = nB; ++ui;
;         if constexpr (ALIGN_EPI) { if (wr == 1) PG8_BAR; }
;     __device__ __forceinline__ void operator()(const f32x4 (&acc)[2][2][4][2], const Unit& u, int wr, int wc, int fr, int fq) const {
;     ...
;                 for (int bj = 0; bj < 2; ++bj) {
;                     const f32x4 x0 = acc[ai][bj][m][0], x1 = acc[ai][bj][m][1]; f32x4 za, zb;
; #pragma unroll
;                     for (int e = 0; e < 4; ++e) {
;                         const float s1 = __shfl_xor(x1[e], 8), s0 = __shfl_xor(x0[e], 8);
;                         za[e] = hi8 ? s1 : x0[e];
;                         zb[e] = hi8 ? x1[e] : s0; }
;                     const f32x4 ba = *(const f32x4*)(base + offA + bj * HALF), bb = *(const f32x4*)(base + offB + bj * HALF);
;                     *(f32x4*)(out + offA + bj * HALF) = ba + gs[bj] * za;
;                     *(f32x4*)(out + offB + bj * HALF) = bb + gs[bj] * zb; } }
	v_pk_fma_f32 v[42:43], v[106:107], v[40:41], v[70:71]
	v_pk_fma_f32 v[40:41], v[104:105], v[44:45], v[68:69]
	v_lshl_add_u64 v[86:87], v[148:149], 0, s[18:19]
	global_store_dwordx4 v[92:93], v[40:43], off sc1
	global_load_dwordx4 v[40:43], v[86:87], off offset:512 nt
	s_waitcnt vmcnt(11)
	v_pk_fma_f32 v[46:47], v[106:107], v[46:47], v[78:79]
	v_lshl_add_u64 v[78:79], v[148:149], 0, s[20:21]
	global_load_dwordx4 v[48:51], v[78:79], off offset:512 nt
	ds_bpermute_b32 v68, v153, v32
	ds_bpermute_b32 v69, v153, v36
	ds_bpermute_b32 v70, v153, v33
	v_pk_fma_f32 v[44:45], v[104:105], v[82:83], v[76:77]
	v_add_co_u32_e32 v82, vcc, s62, v148
	global_store_dwordx4 v[94:95], v[44:47], off sc1
	s_nop 0
	v_addc_co_u32_e32 v83, vcc, 0, v149, vcc
	v_add_co_u32_e32 v88, vcc, s63, v148
	global_load_dwordx4 v[44:47], v[82:83], off nt
	s_nop 0
	v_addc_co_u32_e32 v89, vcc, 0, v149, vcc
	s_waitcnt lgkmcnt(2)
	v_cndmask_b32_e64 v36, v68, v36, s[0:1]
	s_waitcnt lgkmcnt(1)
	v_cndmask_b32_e64 v76, v32, v69, s[0:1]
	ds_bpermute_b32 v32, v153, v37
	s_waitcnt lgkmcnt(1)
	v_cndmask_b32_e64 v37, v70, v37, s[0:1]
	global_load_dwordx4 v[68:71], v[88:89], off nt
	ds_bpermute_b32 v92, v153, v35
	ds_bpermute_b32 v93, v153, v39
	s_waitcnt lgkmcnt(2)
	v_cndmask_b32_e64 v77, v33, v32, s[0:1]
	v_cndmask_b32_e64 v32, v90, v38, s[0:1]
	v_cndmask_b32_e64 v38, v34, v91, s[0:1]
	s_waitcnt lgkmcnt(1)
	v_cndmask_b32_e64 v33, v92, v39, s[0:1]
	s_waitcnt lgkmcnt(0)
	v_cndmask_b32_e64 v39, v35, v93, s[0:1]
	s_waitcnt vmcnt(11)
	v_pk_fma_f32 v[34:35], v[110:111], v[32:33], v[58:59]
	v_pk_fma_f32 v[32:33], v[108:109], v[36:37], v[56:57]
	ds_bpermute_b32 v36, v153, v24
	ds_bpermute_b32 v37, v153, v28
	global_store_dwordx4 v[52:53], v[32:35], off offset:512 sc1
	v_lshl_add_u64 v[56:57], v[148:149], 0, s[22:23]
	v_lshl_add_u64 v[58:59], v[148:149], 0, s[24:25]
	s_waitcnt vmcnt(11)
	v_pk_fma_f32 v[34:35], v[110:111], v[38:39], v[62:63]
	v_pk_fma_f32 v[32:33], v[108:109], v[76:77], v[60:61]
	global_store_dwordx4 v[84:85], v[32:35], off offset:512 sc1
	global_load_dwordx4 v[32:35], v[56:57], off offset:512 nt
	s_waitcnt lgkmcnt(1)
	v_cndmask_b32_e64 v28, v36, v28, s[0:1]
	s_waitcnt lgkmcnt(0)
	v_cndmask_b32_e64 v52, v24, v37, s[0:1]
	global_load_dwordx4 v[36:39], v[58:59], off offset:512 nt
	ds_bpermute_b32 v24, v153, v25
	ds_bpermute_b32 v53, v153, v29
	ds_bpermute_b32 v61, v153, v27
	ds_bpermute_b32 v60, v153, v30
	ds_bpermute_b32 v62, v153, v31
	s_waitcnt lgkmcnt(4)
	v_cndmask_b32_e64 v29, v24, v29, s[0:1]
	ds_bpermute_b32 v24, v153, v26
	s_waitcnt lgkmcnt(4)
	v_cndmask_b32_e64 v53, v25, v53, s[0:1]
	s_waitcnt lgkmcnt(3)
	v_cndmask_b32_e64 v25, v61, v31, s[0:1]
	s_waitcnt lgkmcnt(1)
	v_cndmask_b32_e64 v31, v27, v62, s[0:1]
	s_andn2_b64 vcc, exec, s[2:3]
	s_waitcnt lgkmcnt(0)
	v_cndmask_b32_e64 v24, v24, v30, s[0:1]
	v_cndmask_b32_e64 v30, v26, v60, s[0:1]
	s_waitcnt vmcnt(12)
	v_pk_fma_f32 v[26:27], v[106:107], v[24:25], v[66:67]
	v_pk_fma_f32 v[24:25], v[104:105], v[28:29], v[64:65]
	ds_bpermute_b32 v28, v153, v8
	ds_bpermute_b32 v29, v153, v16
	global_store_dwordx4 v[54:55], v[24:27], off sc1
	s_mov_b64 s[2:3], -1
	s_waitcnt lgkmcnt(1)
	v_cndmask_b32_e64 v16, v28, v16, s[0:1]
	s_waitcnt vmcnt(11)
	v_pk_fma_f32 v[26:27], v[106:107], v[30:31], v[74:75]
	v_pk_fma_f32 v[24:25], v[104:105], v[52:53], v[72:73]
	ds_bpermute_b32 v30, v153, v9
	global_store_dwordx4 v[80:81], v[24:27], off sc1
	ds_bpermute_b32 v26, v153, v10
	ds_bpermute_b32 v28, v153, v11
	s_waitcnt lgkmcnt(3)
	v_cndmask_b32_e64 v24, v8, v29, s[0:1]
	ds_bpermute_b32 v8, v153, v17
	ds_bpermute_b32 v27, v153, v18
	ds_bpermute_b32 v29, v153, v19
	s_waitcnt lgkmcnt(5)
	v_cndmask_b32_e64 v17, v30, v17, s[0:1]
	s_waitcnt lgkmcnt(2)
	v_cndmask_b32_e64 v25, v9, v8, s[0:1]
	v_cndmask_b32_e64 v8, v26, v18, s[0:1]
	v_cndmask_b32_e64 v9, v28, v19, s[0:1]
	s_waitcnt lgkmcnt(1)
	v_cndmask_b32_e64 v18, v10, v27, s[0:1]
	s_waitcnt lgkmcnt(0)
	v_cndmask_b32_e64 v19, v11, v29, s[0:1]
	s_waitcnt vmcnt(10)
	v_pk_fma_f32 v[10:11], v[110:111], v[8:9], v[42:43]
	v_pk_fma_f32 v[8:9], v[108:109], v[16:17], v[40:41]
	ds_bpermute_b32 v17, v153, v20
	global_store_dwordx4 v[86:87], v[8:11], off offset:512 sc1
	ds_bpermute_b32 v16, v153, v12
	s_waitcnt lgkmcnt(1)
	v_cndmask_b32_e64 v12, v12, v17, s[0:1]
	s_waitcnt vmcnt(10)
	v_pk_fma_f32 v[10:11], v[110:111], v[18:19], v[50:51]
	ds_bpermute_b32 v18, v153, v13
	v_pk_fma_f32 v[8:9], v[108:109], v[24:25], v[48:49]
	global_store_dwordx4 v[78:79], v[8:11], off offset:512 sc1
	ds_bpermute_b32 v10, v153, v21
	ds_bpermute_b32 v11, v153, v14
	ds_bpermute_b32 v17, v153, v15
	s_waitcnt lgkmcnt(4)
	v_cndmask_b32_e64 v8, v16, v20, s[0:1]
	s_waitcnt lgkmcnt(3)
	v_cndmask_b32_e64 v9, v18, v21, s[0:1]
	ds_bpermute_b32 v16, v153, v22
	ds_bpermute_b32 v18, v153, v23
	s_waitcnt lgkmcnt(4)
	v_cndmask_b32_e64 v13, v13, v10, s[0:1]
	s_waitcnt lgkmcnt(3)
	v_cndmask_b32_e64 v10, v11, v22, s[0:1]
	s_waitcnt lgkmcnt(2)
	v_cndmask_b32_e64 v11, v17, v23, s[0:1]
	s_waitcnt lgkmcnt(1)
	v_cndmask_b32_e64 v14, v14, v16, s[0:1]
	s_waitcnt lgkmcnt(0)
	v_cndmask_b32_e64 v15, v15, v18, s[0:1]
	s_waitcnt vmcnt(9)
	v_pk_fma_f32 v[10:11], v[106:107], v[10:11], v[46:47]
	v_pk_fma_f32 v[8:9], v[104:105], v[8:9], v[44:45]
	global_store_dwordx4 v[82:83], v[8:11], off sc1
	s_waitcnt vmcnt(9)
	s_nop 0
	v_pk_fma_f32 v[10:11], v[106:107], v[14:15], v[70:71]
	ds_bpermute_b32 v15, v153, v4
	v_pk_fma_f32 v[8:9], v[104:105], v[12:13], v[68:69]
	ds_bpermute_b32 v12, v153, v1
	ds_bpermute_b32 v14, v153, v0
	global_store_dwordx4 v[88:89], v[8:11], off sc1
	ds_bpermute_b32 v10, v153, v2
	ds_bpermute_b32 v11, v153, v6
	s_waitcnt lgkmcnt(4)
	v_cndmask_b32_e64 v8, v0, v15, s[0:1]
	ds_bpermute_b32 v0, v153, v5
	s_waitcnt lgkmcnt(4)
	v_cndmask_b32_e64 v5, v12, v5, s[0:1]
	ds_bpermute_b32 v12, v153, v3
	ds_bpermute_b32 v13, v153, v7
	s_waitcnt lgkmcnt(5)
	v_cndmask_b32_e64 v4, v14, v4, s[0:1]
	s_waitcnt lgkmcnt(2)
	v_cndmask_b32_e64 v9, v1, v0, s[0:1]
	v_cndmask_b32_e64 v0, v10, v6, s[0:1]
	s_waitcnt lgkmcnt(1)
	v_cndmask_b32_e64 v1, v12, v7, s[0:1]
	v_cndmask_b32_e64 v6, v2, v11, s[0:1]
	s_waitcnt lgkmcnt(0)
	v_cndmask_b32_e64 v7, v3, v13, s[0:1]
	s_waitcnt vmcnt(7)
	v_pk_fma_f32 v[2:3], v[110:111], v[0:1], v[34:35]
	v_pk_fma_f32 v[0:1], v[108:109], v[4:5], v[32:33]
	global_store_dwordx4 v[56:57], v[0:3], off offset:512 sc1
	s_waitcnt vmcnt(7)
	s_nop 0
	v_pk_fma_f32 v[2:3], v[110:111], v[6:7], v[38:39]
	v_pk_fma_f32 v[0:1], v[108:109], v[8:9], v[36:37]
	global_store_dwordx4 v[58:59], v[0:3], off offset:512 sc1
	s_cbranch_vccnz .LBB0_808
	s_andn2_b64 vcc, exec, s[4:5]
	s_cbranch_vccnz .LBB0_807
	s_barrier
	s_branch .LBB0_807
